# same increment relocation applied to the W_o and second gate GEMM K-loops (counters held in vcc halves)
# baseline (speedup 1.0000x reference)
; #define PG8_STAGE(bufoff, gbase, voff) do { _Pragma("unroll") for (int _i = 0; _i < 2; ++_i) \
;         __builtin_amdgcn_global_load_lds((const unsigned*)((const char*)(gbase) + (voff)[_i]), (PG8_LAS unsigned*)(lds + (bufoff) + ldsw + _i * 8192), 16, 0, 0); } while (0)
; #define PG8_LDA(dst, b, h) do { _Pragma("unroll") for (int m = 0; m < 4; ++m) _Pragma("unroll") for (int k = 0; k < 2; ++k) dst[m][k] = *(const PG8_LAS bf16x8*)(lds + PG8_SA(b, h) + aoff + m * 2048 + k * 1024); } while (0)
; #define PG8_LDB(dst, b, h) do { _Pragma("unroll") for (int n = 0; n < 2; ++n) _Pragma("unroll") for (int k = 0; k < 2; ++k) dst[n][k] = *(const PG8_LAS bf16x8*)(lds + PG8_SB(b, h) + boff + n * 2048 + k * 1024); } while (0)
; #define PG8_MMA(ai, bj, At, Bt) do { __builtin_amdgcn_s_setprio(1); _Pragma("unroll") for (int m = 0; m < 4; ++m) _Pragma("unroll") for (int n = 0; n < 2; ++n) _Pragma("unroll") for (int k = 0; k < 2; ++k) \
;         acc[ai][bj][m][n] = __builtin_amdgcn_mfma_f32_16x16x32_bf16(Bt[n][k], At[m][k], acc[ai][bj][m][n], 0, 0, 0); __builtin_amdgcn_s_setprio(0); } while (0)
; #define PG8_WAIT_V(n) asm volatile("s_waitcnt vmcnt(" #n ")" ::: "memory")
; template <class Epi, class Sched, bool STAMP = false>
; __device__ __forceinline__ void gemm_phase(PG8_LAS unsigned char* lds, const Gemm g, const Sched& S, const Epi& E, unsigned long long* stamps) {
;     ...
;             const bool last = (t == nt - 2);
;             const char* a1 = cA + (size_t)(t + 1) * kstep;
;             const char* a2 = last ? nA : cA + (size_t)(t + 2) * kstep; const char* b2 = last ? nB : cB + (size_t)(t + 2) * kstep;
;             const char* a3 = a2 + kstep; const char* b3 = b2 + kstep;
;             if (last && has_next) S.a_ready(nxt);
;             PG8_LDB(B0, 0, 0); PG8_SCHED; PG8_LDA(At, 0, 0); PG8_STAGE(PG8_SA(1, 1), a1 + hstep, voffA);
;             PG8_WAIT_L(8); PG8_BAR; PG8_WAIT_L(0); PG8_MMA(0, 0, At, B0); PG8_BAR; PG8_SCHED;
;             PG8_LDB(B1, 0, 1); PG8_STAGE(PG8_SB(0, 0), b2, voffB);
;             PG8_BAR; PG8_WAIT_L(0); PG8_MMA(0, 1, At, B1); PG8_BAR;
;             PG8_LDA(At, 0, 1); PG8_STAGE(PG8_SA(0, 0), a2, voffA);
;             PG8_BAR; PG8_WAIT_L(0); PG8_MMA(1, 0, At, B0); PG8_BAR; PG8_SCHED;
;             PG8_STAGE(PG8_SB(0, 1), b2 + hstep, voffB);
;             PG8_WAIT_V(6); PG8_BAR; PG8_MMA(1, 1, At, B1); PG8_BAR;
.LBB0_141:
	s_add_u32 s48, s44, 0x100
	s_addc_u32 s49, s45, 0
	s_add_i32 s14, 0, 0x10000
	ds_read_b128 v[156:159], v248
	ds_read_b128 v[160:163], v248 offset:1024
	ds_read_b128 v[170:173], v248 offset:2048
	ds_read_b128 v[174:177], v248 offset:3072
	s_cmp_eq_u32 s39, 12
	s_cselect_b32 s59, s23, s49
	s_cselect_b32 s58, s31, s48
	s_cselect_b32 s57, s21, s38
	s_cselect_b32 s56, vcc_lo, vcc_hi
	s_add_i32 m0, s37, 0xc000
	ds_read_b128 v[178:181], v168
	ds_read_b128 v[192:195], v168 offset:1024
	ds_read_b128 v[196:199], v168 offset:2048
	ds_read_b128 v[200:203], v168 offset:3072
	ds_read_b128 v[204:207], v168 offset:4096
	ds_read_b128 v[208:211], v168 offset:5120
	ds_read_b128 v[212:215], v168 offset:6144
	global_load_lds_dwordx4 v152, s[44:45]
	s_add_i32 m0, s37, 0xe000
	ds_read_b128 v[216:219], v168 offset:7168
	global_load_lds_dwordx4 v154, s[44:45]
	s_waitcnt lgkmcnt(8)
	s_barrier
	s_waitcnt lgkmcnt(0)
	v_mfma_f32_16x16x32_bf16 v[124:127], v[156:159], v[178:181], v[124:127]
	v_mfma_f32_16x16x32_bf16 v[120:123], v[170:173], v[178:181], v[120:123]
	v_mfma_f32_16x16x32_bf16 v[108:111], v[156:159], v[196:199], v[108:111]
	v_mfma_f32_16x16x32_bf16 v[104:107], v[170:173], v[196:199], v[104:107]
	v_mfma_f32_16x16x32_bf16 v[92:95], v[156:159], v[204:207], v[92:95]
	v_mfma_f32_16x16x32_bf16 v[88:91], v[170:173], v[204:207], v[88:91]
	v_mfma_f32_16x16x32_bf16 v[76:79], v[156:159], v[212:215], v[76:79]
	v_mfma_f32_16x16x32_bf16 v[72:75], v[170:173], v[212:215], v[72:75]
	v_mfma_f32_16x16x32_bf16 v[124:127], v[160:163], v[192:195], v[124:127]
	v_mfma_f32_16x16x32_bf16 v[120:123], v[174:177], v[192:195], v[120:123]
	v_mfma_f32_16x16x32_bf16 v[108:111], v[160:163], v[200:203], v[108:111]
	v_mfma_f32_16x16x32_bf16 v[104:107], v[174:177], v[200:203], v[104:107]
	v_mfma_f32_16x16x32_bf16 v[92:95], v[160:163], v[208:211], v[92:95]
	v_mfma_f32_16x16x32_bf16 v[88:91], v[174:177], v[208:211], v[88:91]
	v_mfma_f32_16x16x32_bf16 v[76:79], v[160:163], v[216:219], v[76:79]
	v_mfma_f32_16x16x32_bf16 v[72:75], v[174:177], v[216:219], v[72:75]
	s_barrier
	s_add_i32 s16, 0, 0x14000
	s_add_i32 s14, s14, s64
	s_mov_b32 m0, s14
	ds_read_b128 v[220:223], v249
	ds_read_b128 v[224:227], v249 offset:1024
	ds_read_b128 v[228:231], v249 offset:2048
	global_load_lds_dwordx4 v148, s[56:57]
	s_add_i32 m0, s14, 0x2000
	ds_read_b128 v[232:235], v249 offset:3072
	global_load_lds_dwordx4 v150, s[56:57]
	s_barrier
	s_waitcnt lgkmcnt(0)
	v_mfma_f32_16x16x32_bf16 v[116:119], v[220:223], v[178:181], v[116:119]
	v_mfma_f32_16x16x32_bf16 v[112:115], v[228:231], v[178:181], v[112:115]
	v_mfma_f32_16x16x32_bf16 v[100:103], v[220:223], v[196:199], v[100:103]
	v_mfma_f32_16x16x32_bf16 v[96:99], v[228:231], v[196:199], v[96:99]
	v_mfma_f32_16x16x32_bf16 v[84:87], v[220:223], v[204:207], v[84:87]
	v_mfma_f32_16x16x32_bf16 v[80:83], v[228:231], v[204:207], v[80:83]
	v_mfma_f32_16x16x32_bf16 v[68:71], v[220:223], v[212:215], v[68:71]
	v_mfma_f32_16x16x32_bf16 v[64:67], v[228:231], v[212:215], v[64:67]
	v_mfma_f32_16x16x32_bf16 v[116:119], v[224:227], v[192:195], v[116:119]
	v_mfma_f32_16x16x32_bf16 v[112:115], v[232:235], v[192:195], v[112:115]
	v_mfma_f32_16x16x32_bf16 v[100:103], v[224:227], v[200:203], v[100:103]
	v_mfma_f32_16x16x32_bf16 v[96:99], v[232:235], v[200:203], v[96:99]
	v_mfma_f32_16x16x32_bf16 v[84:87], v[224:227], v[208:211], v[84:87]
	v_mfma_f32_16x16x32_bf16 v[80:83], v[232:235], v[208:211], v[80:83]
	v_mfma_f32_16x16x32_bf16 v[68:71], v[224:227], v[216:219], v[68:71]
	v_mfma_f32_16x16x32_bf16 v[64:67], v[232:235], v[216:219], v[64:67]
	s_mov_b32 m0, s37
	s_barrier
	ds_read_b128 v[178:181], v168 offset:16384
	ds_read_b128 v[192:195], v168 offset:17408
	ds_read_b128 v[196:199], v168 offset:18432
	ds_read_b128 v[200:203], v168 offset:19456
	ds_read_b128 v[204:207], v168 offset:20480
	ds_read_b128 v[208:211], v168 offset:21504
	ds_read_b128 v[212:215], v168 offset:22528
	global_load_lds_dwordx4 v148, s[58:59]
	s_mov_b32 m0, s65
	ds_read_b128 v[216:219], v168 offset:23552
	global_load_lds_dwordx4 v150, s[58:59]
	s_barrier
	s_waitcnt lgkmcnt(0)
	v_mfma_f32_16x16x32_bf16 v[60:63], v[156:159], v[178:181], v[60:63]
	v_mfma_f32_16x16x32_bf16 v[56:59], v[170:173], v[178:181], v[56:59]
	v_mfma_f32_16x16x32_bf16 v[44:47], v[156:159], v[196:199], v[44:47]
	v_mfma_f32_16x16x32_bf16 v[40:43], v[170:173], v[196:199], v[40:43]
	v_mfma_f32_16x16x32_bf16 v[28:31], v[156:159], v[204:207], v[28:31]
	v_mfma_f32_16x16x32_bf16 v[24:27], v[170:173], v[204:207], v[24:27]
	v_mfma_f32_16x16x32_bf16 v[12:15], v[156:159], v[212:215], v[12:15]
	v_mfma_f32_16x16x32_bf16 v[8:11], v[170:173], v[212:215], v[8:11]
	v_mfma_f32_16x16x32_bf16 v[60:63], v[160:163], v[192:195], v[60:63]
	v_mfma_f32_16x16x32_bf16 v[56:59], v[174:177], v[192:195], v[56:59]
	v_mfma_f32_16x16x32_bf16 v[44:47], v[160:163], v[200:203], v[44:47]
	v_mfma_f32_16x16x32_bf16 v[40:43], v[174:177], v[200:203], v[40:43]
	v_mfma_f32_16x16x32_bf16 v[28:31], v[160:163], v[208:211], v[28:31]
	v_mfma_f32_16x16x32_bf16 v[24:27], v[174:177], v[208:211], v[24:27]
	v_mfma_f32_16x16x32_bf16 v[12:15], v[160:163], v[216:219], v[12:15]
	v_mfma_f32_16x16x32_bf16 v[8:11], v[174:177], v[216:219], v[8:11]
	s_barrier
	s_add_u32 s14, s56, 0x40000
	s_addc_u32 s15, s57, 0
	s_add_i32 s16, s16, s64
	s_mov_b32 m0, s16
	s_nop 0
	global_load_lds_dwordx4 v148, s[14:15]
	s_add_i32 m0, s16, 0x2000
	s_nop 0
	global_load_lds_dwordx4 v150, s[14:15]
	s_add_i32 s39, s39, 2
	s_add_u32 vcc_hi, vcc_hi, 0x100
	s_addc_u32 s38, s38, 0
	s_waitcnt vmcnt(6)
	s_barrier
; #define PG8_STAGE(bufoff, gbase, voff) do { _Pragma("unroll") for (int _i = 0; _i < 2; ++_i) \
;         __builtin_amdgcn_global_load_lds((const unsigned*)((const char*)(gbase) + (voff)[_i]), (PG8_LAS unsigned*)(lds + (bufoff) + ldsw + _i * 8192), 16, 0, 0); } while (0)
; #define PG8_LDA(dst, b, h) do { _Pragma("unroll") for (int m = 0; m < 4; ++m) _Pragma("unroll") for (int k = 0; k < 2; ++k) dst[m][k] = *(const PG8_LAS bf16x8*)(lds + PG8_SA(b, h) + aoff + m * 2048 + k * 1024); } while (0)
; #define PG8_LDB(dst, b, h) do { _Pragma("unroll") for (int n = 0; n < 2; ++n) _Pragma("unroll") for (int k = 0; k < 2; ++k) dst[n][k] = *(const PG8_LAS bf16x8*)(lds + PG8_SB(b, h) + boff + n * 2048 + k * 1024); } while (0)
; #define PG8_MMA(ai, bj, At, Bt) do { __builtin_amdgcn_s_setprio(1); _Pragma("unroll") for (int m = 0; m < 4; ++m) _Pragma("unroll") for (int n = 0; n < 2; ++n) _Pragma("unroll") for (int k = 0; k < 2; ++k) \
;         acc[ai][bj][m][n] = __builtin_amdgcn_mfma_f32_16x16x32_bf16(Bt[n][k], At[m][k], acc[ai][bj][m][n], 0, 0, 0); __builtin_amdgcn_s_setprio(0); } while (0)
; #define PG8_WAIT_V(n) asm volatile("s_waitcnt vmcnt(" #n ")" ::: "memory")
; #define PG8_WAIT_L(n) asm volatile("s_waitcnt lgkmcnt(" #n ")" ::: "memory")
; #define PG8_BAR __builtin_amdgcn_s_barrier()
; #define PG8_SCHED __builtin_amdgcn_sched_barrier(0)
; template <class Epi, class Sched, bool STAMP = false>
; __device__ __forceinline__ void gemm_phase(PG8_LAS unsigned char* lds, const Gemm g, const Sched& S, const Epi& E, unsigned long long* stamps) {
;     ...
;             PG8_WAIT_V(6); PG8_BAR; PG8_MMA(1, 1, At, B1); PG8_BAR;
;             PG8_LDB(B0, 1, 0); PG8_SCHED; PG8_LDA(At, 1, 0); PG8_STAGE(PG8_SA(0, 1), a2 + hstep, voffA);
;             PG8_WAIT_L(8); PG8_BAR; PG8_WAIT_L(0); PG8_MMA(0, 0, At, B0); PG8_BAR; PG8_SCHED;
;             PG8_LDB(B1, 1, 1); PG8_STAGE(PG8_SB(1, 0), b3, voffB);
;             PG8_BAR; PG8_WAIT_L(0); PG8_MMA(0, 1, At, B1); PG8_BAR;
;             PG8_LDA(At, 1, 1); PG8_STAGE(PG8_SA(1, 0), a3, voffA);
	v_mfma_f32_16x16x32_bf16 v[52:55], v[220:223], v[178:181], v[52:55]
	v_mfma_f32_16x16x32_bf16 v[48:51], v[228:231], v[178:181], v[48:51]
	v_mfma_f32_16x16x32_bf16 v[36:39], v[220:223], v[196:199], v[36:39]
	v_mfma_f32_16x16x32_bf16 v[32:35], v[228:231], v[196:199], v[32:35]
	v_mfma_f32_16x16x32_bf16 v[20:23], v[220:223], v[204:207], v[20:23]
	v_mfma_f32_16x16x32_bf16 v[16:19], v[228:231], v[204:207], v[16:19]
	v_mfma_f32_16x16x32_bf16 v[4:7], v[220:223], v[212:215], v[4:7]
	v_mfma_f32_16x16x32_bf16 v[0:3], v[228:231], v[212:215], v[0:3]
	v_mfma_f32_16x16x32_bf16 v[52:55], v[224:227], v[192:195], v[52:55]
	v_mfma_f32_16x16x32_bf16 v[48:51], v[232:235], v[192:195], v[48:51]
	v_mfma_f32_16x16x32_bf16 v[36:39], v[224:227], v[200:203], v[36:39]
	v_mfma_f32_16x16x32_bf16 v[32:35], v[232:235], v[200:203], v[32:35]
	v_mfma_f32_16x16x32_bf16 v[20:23], v[224:227], v[208:211], v[20:23]
	v_mfma_f32_16x16x32_bf16 v[16:19], v[232:235], v[208:211], v[16:19]
	v_mfma_f32_16x16x32_bf16 v[4:7], v[224:227], v[216:219], v[4:7]
	v_mfma_f32_16x16x32_bf16 v[0:3], v[232:235], v[216:219], v[0:3]
	s_add_i32 s16, 0, 0x18000
	s_barrier
	ds_read_b128 v[156:159], v250
	ds_read_b128 v[160:163], v250 offset:1024
	ds_read_b128 v[170:173], v250 offset:2048
	ds_read_b128 v[174:177], v250 offset:3072
	s_add_u32 s14, s58, 0x40000
	s_addc_u32 s15, s59, 0
	s_mov_b32 m0, s76
	ds_read_b128 v[178:181], v168 offset:32768
	ds_read_b128 v[192:195], v168 offset:33792
	ds_read_b128 v[196:199], v168 offset:34816
	ds_read_b128 v[200:203], v168 offset:35840
	ds_read_b128 v[204:207], v168 offset:36864
	ds_read_b128 v[208:211], v168 offset:37888
	ds_read_b128 v[212:215], v168 offset:38912
	global_load_lds_dwordx4 v148, s[14:15]
	s_mov_b32 m0, s77
	ds_read_b128 v[216:219], v168 offset:39936
	global_load_lds_dwordx4 v150, s[14:15]
	s_waitcnt lgkmcnt(8)
	s_barrier
	s_waitcnt lgkmcnt(0)
	v_mfma_f32_16x16x32_bf16 v[124:127], v[156:159], v[178:181], v[124:127]
	v_mfma_f32_16x16x32_bf16 v[120:123], v[170:173], v[178:181], v[120:123]
	v_mfma_f32_16x16x32_bf16 v[108:111], v[156:159], v[196:199], v[108:111]
	v_mfma_f32_16x16x32_bf16 v[104:107], v[170:173], v[196:199], v[104:107]
	v_mfma_f32_16x16x32_bf16 v[92:95], v[156:159], v[204:207], v[92:95]
	v_mfma_f32_16x16x32_bf16 v[88:91], v[170:173], v[204:207], v[88:91]
	v_mfma_f32_16x16x32_bf16 v[76:79], v[156:159], v[212:215], v[76:79]
	v_mfma_f32_16x16x32_bf16 v[72:75], v[170:173], v[212:215], v[72:75]
	v_mfma_f32_16x16x32_bf16 v[124:127], v[160:163], v[192:195], v[124:127]
	v_mfma_f32_16x16x32_bf16 v[120:123], v[174:177], v[192:195], v[120:123]
	v_mfma_f32_16x16x32_bf16 v[108:111], v[160:163], v[200:203], v[108:111]
	v_mfma_f32_16x16x32_bf16 v[104:107], v[174:177], v[200:203], v[104:107]
	v_mfma_f32_16x16x32_bf16 v[92:95], v[160:163], v[208:211], v[92:95]
	v_mfma_f32_16x16x32_bf16 v[88:91], v[174:177], v[208:211], v[88:91]
	v_mfma_f32_16x16x32_bf16 v[76:79], v[160:163], v[216:219], v[76:79]
	v_mfma_f32_16x16x32_bf16 v[72:75], v[174:177], v[216:219], v[72:75]
	s_barrier
	s_add_i32 s17, 0, 0x1c000
	s_add_i32 s14, s16, s64
	s_mov_b32 m0, s14
	ds_read_b128 v[220:223], v251
	ds_read_b128 v[224:227], v251 offset:1024
	ds_read_b128 v[228:231], v251 offset:2048
	global_load_lds_dwordx4 v244, s[56:57]
	s_add_i32 m0, s14, 0x2000
	ds_read_b128 v[232:235], v251 offset:3072
	global_load_lds_dwordx4 v245, s[56:57]
	s_barrier
	s_waitcnt lgkmcnt(0)
	v_mfma_f32_16x16x32_bf16 v[116:119], v[220:223], v[178:181], v[116:119]
	v_mfma_f32_16x16x32_bf16 v[112:115], v[228:231], v[178:181], v[112:115]
	v_mfma_f32_16x16x32_bf16 v[100:103], v[220:223], v[196:199], v[100:103]
	v_mfma_f32_16x16x32_bf16 v[96:99], v[228:231], v[196:199], v[96:99]
	v_mfma_f32_16x16x32_bf16 v[84:87], v[220:223], v[204:207], v[84:87]
	v_mfma_f32_16x16x32_bf16 v[80:83], v[228:231], v[204:207], v[80:83]
	v_mfma_f32_16x16x32_bf16 v[68:71], v[220:223], v[212:215], v[68:71]
	v_mfma_f32_16x16x32_bf16 v[64:67], v[228:231], v[212:215], v[64:67]
	v_mfma_f32_16x16x32_bf16 v[116:119], v[224:227], v[192:195], v[116:119]
	v_mfma_f32_16x16x32_bf16 v[112:115], v[232:235], v[192:195], v[112:115]
	v_mfma_f32_16x16x32_bf16 v[100:103], v[224:227], v[200:203], v[100:103]
	v_mfma_f32_16x16x32_bf16 v[96:99], v[232:235], v[200:203], v[96:99]
	v_mfma_f32_16x16x32_bf16 v[84:87], v[224:227], v[208:211], v[84:87]
	v_mfma_f32_16x16x32_bf16 v[80:83], v[232:235], v[208:211], v[80:83]
	v_mfma_f32_16x16x32_bf16 v[68:71], v[224:227], v[216:219], v[68:71]
	v_mfma_f32_16x16x32_bf16 v[64:67], v[232:235], v[216:219], v[64:67]
	s_mov_b32 m0, s88
	s_barrier
; #define PG8_STAGE(bufoff, gbase, voff) do { _Pragma("unroll") for (int _i = 0; _i < 2; ++_i) \
;         __builtin_amdgcn_global_load_lds((const unsigned*)((const char*)(gbase) + (voff)[_i]), (PG8_LAS unsigned*)(lds + (bufoff) + ldsw + _i * 8192), 16, 0, 0); } while (0)
; #define PG8_MMA(ai, bj, At, Bt) do { __builtin_amdgcn_s_setprio(1); _Pragma("unroll") for (int m = 0; m < 4; ++m) _Pragma("unroll") for (int n = 0; n < 2; ++n) _Pragma("unroll") for (int k = 0; k < 2; ++k) \
;         acc[ai][bj][m][n] = __builtin_amdgcn_mfma_f32_16x16x32_bf16(Bt[n][k], At[m][k], acc[ai][bj][m][n], 0, 0, 0); __builtin_amdgcn_s_setprio(0); } while (0)
; #define PG8_WAIT_V(n) asm volatile("s_waitcnt vmcnt(" #n ")" ::: "memory")
; #define PG8_WAIT_L(n) asm volatile("s_waitcnt lgkmcnt(" #n ")" ::: "memory")
; #define PG8_BAR __builtin_amdgcn_s_barrier()
; #define PG8_SCHED __builtin_amdgcn_sched_barrier(0)
; template <class Epi, class Sched, bool STAMP = false>
; __device__ __forceinline__ void gemm_phase(PG8_LAS unsigned char* lds, const Gemm g, const Sched& S, const Epi& E, unsigned long long* stamps) {
;     ...
;             PG8_BAR; PG8_WAIT_L(0); PG8_MMA(1, 0, At, B0); PG8_BAR; PG8_SCHED;
;             PG8_STAGE(PG8_SB(1, 1), b3 + hstep, voffB);
;             PG8_WAIT_V(6); PG8_BAR; PG8_MMA(1, 1, At, B1); PG8_BAR;
;     __device__ __forceinline__ void operator()(const f32x4 (&acc)[2][2][4][2], const pg8::Unit& u, int wr, int wc, int fr, int fq) const {
;         const int row0 = u.pm * 256 + wr * 64 + fr, col0 = u.pn * 256 + wc * 32 + 4 * fq;
; #pragma unroll
;         for (int ai = 0; ai < 2; ++ai)
; #pragma unroll
;             for (int m = 0; m < 4; ++m) {
;                 const int row = row0 + ai * 128 + m * 16;
;                 float* xp = X + (size_t)row * 1024 + col0; bf16_t* bp = XB + (size_t)row * 1024 + col0;
;                 const float* xi = Xp0 ? (row < T_P ? Xp0 + (size_t)row * 1024 + col0 : Xs0 + (size_t)(row - T_P) * 1024 + col0) : xp;
	ds_read_b128 v[178:181], v168 offset:49152
	ds_read_b128 v[192:195], v168 offset:50176
	ds_read_b128 v[196:199], v168 offset:51200
	ds_read_b128 v[200:203], v168 offset:52224
	ds_read_b128 v[204:207], v168 offset:53248
	ds_read_b128 v[208:211], v168 offset:54272
	ds_read_b128 v[212:215], v168 offset:55296
	global_load_lds_dwordx4 v244, s[58:59]
	s_mov_b32 m0, s89
	ds_read_b128 v[216:219], v168 offset:56320
	global_load_lds_dwordx4 v245, s[58:59]
	s_barrier
	s_waitcnt lgkmcnt(0)
	v_mfma_f32_16x16x32_bf16 v[60:63], v[156:159], v[178:181], v[60:63]
	v_mfma_f32_16x16x32_bf16 v[56:59], v[170:173], v[178:181], v[56:59]
	v_mfma_f32_16x16x32_bf16 v[44:47], v[156:159], v[196:199], v[44:47]
	v_mfma_f32_16x16x32_bf16 v[40:43], v[170:173], v[196:199], v[40:43]
	v_mfma_f32_16x16x32_bf16 v[28:31], v[156:159], v[204:207], v[28:31]
	v_mfma_f32_16x16x32_bf16 v[24:27], v[170:173], v[204:207], v[24:27]
	v_mfma_f32_16x16x32_bf16 v[12:15], v[156:159], v[212:215], v[12:15]
	v_mfma_f32_16x16x32_bf16 v[8:11], v[170:173], v[212:215], v[8:11]
	v_mfma_f32_16x16x32_bf16 v[60:63], v[160:163], v[192:195], v[60:63]
	v_mfma_f32_16x16x32_bf16 v[56:59], v[174:177], v[192:195], v[56:59]
	v_mfma_f32_16x16x32_bf16 v[44:47], v[160:163], v[200:203], v[44:47]
	v_mfma_f32_16x16x32_bf16 v[40:43], v[174:177], v[200:203], v[40:43]
	v_mfma_f32_16x16x32_bf16 v[28:31], v[160:163], v[208:211], v[28:31]
	v_mfma_f32_16x16x32_bf16 v[24:27], v[174:177], v[208:211], v[24:27]
	v_mfma_f32_16x16x32_bf16 v[12:15], v[160:163], v[216:219], v[12:15]
	v_mfma_f32_16x16x32_bf16 v[8:11], v[174:177], v[216:219], v[8:11]
	s_barrier
	s_add_u32 s14, s56, 0x40080
	s_addc_u32 s15, s57, 0
	s_add_i32 s16, s17, s64
	s_mov_b32 m0, s16
	s_nop 0
	global_load_lds_dwordx4 v148, s[14:15]
	s_add_i32 m0, s16, 0x2000
	s_nop 0
	global_load_lds_dwordx4 v150, s[14:15]
	s_waitcnt vmcnt(6)
	s_barrier
	v_mfma_f32_16x16x32_bf16 v[52:55], v[220:223], v[178:181], v[52:55]
	v_mfma_f32_16x16x32_bf16 v[48:51], v[228:231], v[178:181], v[48:51]
	v_mfma_f32_16x16x32_bf16 v[36:39], v[220:223], v[196:199], v[36:39]
	v_mfma_f32_16x16x32_bf16 v[32:35], v[228:231], v[196:199], v[32:35]
	v_mfma_f32_16x16x32_bf16 v[20:23], v[220:223], v[204:207], v[20:23]
	v_mfma_f32_16x16x32_bf16 v[16:19], v[228:231], v[204:207], v[16:19]
	v_mfma_f32_16x16x32_bf16 v[4:7], v[220:223], v[212:215], v[4:7]
	v_mfma_f32_16x16x32_bf16 v[0:3], v[228:231], v[212:215], v[0:3]
	v_mfma_f32_16x16x32_bf16 v[52:55], v[224:227], v[192:195], v[52:55]
	v_mfma_f32_16x16x32_bf16 v[48:51], v[232:235], v[192:195], v[48:51]
	v_mfma_f32_16x16x32_bf16 v[36:39], v[224:227], v[200:203], v[36:39]
	v_mfma_f32_16x16x32_bf16 v[32:35], v[232:235], v[200:203], v[32:35]
	v_mfma_f32_16x16x32_bf16 v[20:23], v[224:227], v[208:211], v[20:23]
	v_mfma_f32_16x16x32_bf16 v[16:19], v[232:235], v[208:211], v[16:19]
	v_mfma_f32_16x16x32_bf16 v[4:7], v[224:227], v[216:219], v[4:7]
	v_mfma_f32_16x16x32_bf16 v[0:3], v[232:235], v[216:219], v[0:3]
	s_cmp_gt_u32 s39, 13
	s_mov_b64 s[44:45], s[48:49]
	s_barrier
	s_cbranch_scc0 .LBB0_141
	v_lshl_add_u32 v158, s30, 8, v139
	v_ashrrev_i32_e32 v159, 31, v158
	v_lshl_or_b32 v156, s36, 8, v167
	v_lshlrev_b64 v[160:161], 12, v[158:159]
	v_ashrrev_i32_e32 v157, 31, v156
	v_lshl_add_u64 v[160:161], s[84:85], 0, v[160:161]
	v_lshl_add_u64 v[160:161], v[156:157], 2, v[160:161]
	v_cndmask_b32_e64 v128, 0, 1, s[12:13]
	v_lshlrev_b64 v[164:165], 10, v[158:159]
	v_cmp_ne_u32_e64 s[44:45], 1, v128
	s_andn2_b64 vcc, exec, s[12:13]
	v_mov_b64_e32 v[162:163], v[160:161]
	v_readlane_b32 s39, v242, 28
	s_movk_i32 s21, 0x3fff
	s_mov_b32 s38, 0x1ffff
	s_cbranch_vccnz .LBB0_148
	v_cmp_lt_i32_e32 vcc, s21, v158
	s_and_saveexec_b64 s[14:15], vcc
	s_xor_b64 s[30:31], exec, s[14:15]
	v_add_u32_e32 v128, 0xffffc000, v158
	v_lshlrev_b64 v[162:163], 12, v[128:129]
	v_lshl_add_u64 v[162:163], s[4:5], 0, v[162:163]
	v_lshl_add_u64 v[162:163], v[156:157], 2, v[162:163]
	s_andn2_saveexec_b64 s[30:31], s[30:31]
	v_lshl_add_u64 v[162:163], v[164:165], 2, s[0:1]
	v_lshl_add_u64 v[162:163], v[156:157], 2, v[162:163]
	s_or_b64 exec, exec, s[30:31]

; #define PG8_STAGE(bufoff, gbase, voff) do { _Pragma("unroll") for (int _i = 0; _i < 2; ++_i) \
;         __builtin_amdgcn_global_load_lds((const unsigned*)((const char*)(gbase) + (voff)[_i]), (PG8_LAS unsigned*)(lds + (bufoff) + ldsw + _i * 8192), 16, 0, 0); } while (0)
; #define PG8_LDA(dst, b, h) do { _Pragma("unroll") for (int m = 0; m < 4; ++m) _Pragma("unroll") for (int k = 0; k < 2; ++k) dst[m][k] = *(const PG8_LAS bf16x8*)(lds + PG8_SA(b, h) + aoff + m * 2048 + k * 1024); } while (0)
; #define PG8_LDB(dst, b, h) do { _Pragma("unroll") for (int n = 0; n < 2; ++n) _Pragma("unroll") for (int k = 0; k < 2; ++k) dst[n][k] = *(const PG8_LAS bf16x8*)(lds + PG8_SB(b, h) + boff + n * 2048 + k * 1024); } while (0)
; #define PG8_MMA(ai, bj, At, Bt) do { __builtin_amdgcn_s_setprio(1); _Pragma("unroll") for (int m = 0; m < 4; ++m) _Pragma("unroll") for (int n = 0; n < 2; ++n) _Pragma("unroll") for (int k = 0; k < 2; ++k) \
;         acc[ai][bj][m][n] = __builtin_amdgcn_mfma_f32_16x16x32_bf16(Bt[n][k], At[m][k], acc[ai][bj][m][n], 0, 0, 0); __builtin_amdgcn_s_setprio(0); } while (0)
; #define PG8_WAIT_V(n) asm volatile("s_waitcnt vmcnt(" #n ")" ::: "memory")
; template <class Epi, class Sched, bool STAMP = false>
; __device__ __forceinline__ void gemm_phase(PG8_LAS unsigned char* lds, const Gemm g, const Sched& S, const Epi& E, unsigned long long* stamps) {
;     ...
;             const bool last = (t == nt - 2);
;             const char* a1 = cA + (size_t)(t + 1) * kstep;
;             const char* a2 = last ? nA : cA + (size_t)(t + 2) * kstep; const char* b2 = last ? nB : cB + (size_t)(t + 2) * kstep;
;             const char* a3 = a2 + kstep; const char* b3 = b2 + kstep;
;             if (last && has_next) S.a_ready(nxt);
;             PG8_LDB(B0, 0, 0); PG8_SCHED; PG8_LDA(At, 0, 0); PG8_STAGE(PG8_SA(1, 1), a1 + hstep, voffA);
;             PG8_WAIT_L(8); PG8_BAR; PG8_WAIT_L(0); PG8_MMA(0, 0, At, B0); PG8_BAR; PG8_SCHED;
;             PG8_LDB(B1, 0, 1); PG8_STAGE(PG8_SB(0, 0), b2, voffB);
;             PG8_BAR; PG8_WAIT_L(0); PG8_MMA(0, 1, At, B1); PG8_BAR;
;             PG8_LDA(At, 0, 1); PG8_STAGE(PG8_SA(0, 0), a2, voffA);
;             PG8_BAR; PG8_WAIT_L(0); PG8_MMA(1, 0, At, B0); PG8_BAR; PG8_SCHED;
;             PG8_STAGE(PG8_SB(0, 1), b2 + hstep, voffB);
;             PG8_WAIT_V(6); PG8_BAR; PG8_MMA(1, 1, At, B1); PG8_BAR;
.LBB0_353:
	s_add_u32 s14, s56, 0xfffc0080
	s_addc_u32 s15, s57, -1
	s_add_i32 s16, 0, 0x10000
	ds_read_b128 v[158:161], v248
	ds_read_b128 v[162:165], v248 offset:1024
	ds_read_b128 v[172:175], v248 offset:2048
	ds_read_b128 v[176:179], v248 offset:3072
	s_cmp_eq_u32 vcc_lo, 12
	s_cselect_b32 s61, s13, s15
	s_cselect_b32 s60, s47, s14
	s_cselect_b32 s59, s27, s77
	s_cselect_b32 s58, s53, s76
	s_add_i32 m0, s89, 0xc000
	ds_read_b128 v[180:183], v171
	ds_read_b128 v[192:195], v171 offset:1024
	ds_read_b128 v[196:199], v171 offset:2048
	ds_read_b128 v[200:203], v171 offset:3072
	ds_read_b128 v[204:207], v171 offset:4096
	ds_read_b128 v[208:211], v171 offset:5120
	ds_read_b128 v[212:215], v171 offset:6144
	global_load_lds_dwordx4 v154, s[56:57]
	s_add_i32 m0, s89, 0xe000
	ds_read_b128 v[216:219], v171 offset:7168
	global_load_lds_dwordx4 v156, s[56:57]
	s_waitcnt lgkmcnt(8)
	s_barrier
	s_waitcnt lgkmcnt(0)
	v_mfma_f32_16x16x32_bf16 v[124:127], v[158:161], v[180:183], v[124:127]
	v_mfma_f32_16x16x32_bf16 v[120:123], v[172:175], v[180:183], v[120:123]
	v_mfma_f32_16x16x32_bf16 v[108:111], v[158:161], v[196:199], v[108:111]
	v_mfma_f32_16x16x32_bf16 v[104:107], v[172:175], v[196:199], v[104:107]
	v_mfma_f32_16x16x32_bf16 v[92:95], v[158:161], v[204:207], v[92:95]
	v_mfma_f32_16x16x32_bf16 v[88:91], v[172:175], v[204:207], v[88:91]
	v_mfma_f32_16x16x32_bf16 v[76:79], v[158:161], v[212:215], v[76:79]
	v_mfma_f32_16x16x32_bf16 v[72:75], v[172:175], v[212:215], v[72:75]
	v_mfma_f32_16x16x32_bf16 v[124:127], v[162:165], v[192:195], v[124:127]
	v_mfma_f32_16x16x32_bf16 v[120:123], v[176:179], v[192:195], v[120:123]
	v_mfma_f32_16x16x32_bf16 v[108:111], v[162:165], v[200:203], v[108:111]
	v_mfma_f32_16x16x32_bf16 v[104:107], v[176:179], v[200:203], v[104:107]
	v_mfma_f32_16x16x32_bf16 v[92:95], v[162:165], v[208:211], v[92:95]
	v_mfma_f32_16x16x32_bf16 v[88:91], v[176:179], v[208:211], v[88:91]
	v_mfma_f32_16x16x32_bf16 v[76:79], v[162:165], v[216:219], v[76:79]
	v_mfma_f32_16x16x32_bf16 v[72:75], v[176:179], v[216:219], v[72:75]
	s_barrier
	s_add_i32 s17, 0, 0x14000
	s_add_i32 s14, s16, s88
	s_mov_b32 m0, s14
	ds_read_b128 v[220:223], v249
	ds_read_b128 v[224:227], v249 offset:1024
	ds_read_b128 v[228:231], v249 offset:2048
	global_load_lds_dwordx4 v128, s[58:59]
	s_add_i32 m0, s14, 0x2000
	ds_read_b128 v[232:235], v249 offset:3072
	global_load_lds_dwordx4 v152, s[58:59]
	s_barrier
	s_waitcnt lgkmcnt(0)
	v_mfma_f32_16x16x32_bf16 v[116:119], v[220:223], v[180:183], v[116:119]
	v_mfma_f32_16x16x32_bf16 v[112:115], v[228:231], v[180:183], v[112:115]
	v_mfma_f32_16x16x32_bf16 v[100:103], v[220:223], v[196:199], v[100:103]
	v_mfma_f32_16x16x32_bf16 v[96:99], v[228:231], v[196:199], v[96:99]
	v_mfma_f32_16x16x32_bf16 v[84:87], v[220:223], v[204:207], v[84:87]
	v_mfma_f32_16x16x32_bf16 v[80:83], v[228:231], v[204:207], v[80:83]
	v_mfma_f32_16x16x32_bf16 v[68:71], v[220:223], v[212:215], v[68:71]
	v_mfma_f32_16x16x32_bf16 v[64:67], v[228:231], v[212:215], v[64:67]
	v_mfma_f32_16x16x32_bf16 v[116:119], v[224:227], v[192:195], v[116:119]
	v_mfma_f32_16x16x32_bf16 v[112:115], v[232:235], v[192:195], v[112:115]
	v_mfma_f32_16x16x32_bf16 v[100:103], v[224:227], v[200:203], v[100:103]
	v_mfma_f32_16x16x32_bf16 v[96:99], v[232:235], v[200:203], v[96:99]
	v_mfma_f32_16x16x32_bf16 v[84:87], v[224:227], v[208:211], v[84:87]
	v_mfma_f32_16x16x32_bf16 v[80:83], v[232:235], v[208:211], v[80:83]
	v_mfma_f32_16x16x32_bf16 v[68:71], v[224:227], v[216:219], v[68:71]
	v_mfma_f32_16x16x32_bf16 v[64:67], v[232:235], v[216:219], v[64:67]
	s_mov_b32 m0, s89
	s_barrier
	ds_read_b128 v[180:183], v171 offset:16384
	ds_read_b128 v[192:195], v171 offset:17408
	ds_read_b128 v[196:199], v171 offset:18432
	ds_read_b128 v[200:203], v171 offset:19456
	ds_read_b128 v[204:207], v171 offset:20480
	ds_read_b128 v[208:211], v171 offset:21504
	ds_read_b128 v[212:215], v171 offset:22528
	global_load_lds_dwordx4 v148, s[60:61]
	s_mov_b32 m0, s96
	ds_read_b128 v[216:219], v171 offset:23552
	global_load_lds_dwordx4 v150, s[60:61]
	s_barrier
	s_waitcnt lgkmcnt(0)
	v_mfma_f32_16x16x32_bf16 v[60:63], v[158:161], v[180:183], v[60:63]
	v_mfma_f32_16x16x32_bf16 v[56:59], v[172:175], v[180:183], v[56:59]
	v_mfma_f32_16x16x32_bf16 v[44:47], v[158:161], v[196:199], v[44:47]
	v_mfma_f32_16x16x32_bf16 v[40:43], v[172:175], v[196:199], v[40:43]
	v_mfma_f32_16x16x32_bf16 v[28:31], v[158:161], v[204:207], v[28:31]
	v_mfma_f32_16x16x32_bf16 v[24:27], v[172:175], v[204:207], v[24:27]
	v_mfma_f32_16x16x32_bf16 v[12:15], v[158:161], v[212:215], v[12:15]
	v_mfma_f32_16x16x32_bf16 v[8:11], v[172:175], v[212:215], v[8:11]
	v_mfma_f32_16x16x32_bf16 v[60:63], v[162:165], v[192:195], v[60:63]
	v_mfma_f32_16x16x32_bf16 v[56:59], v[176:179], v[192:195], v[56:59]
	v_mfma_f32_16x16x32_bf16 v[44:47], v[162:165], v[200:203], v[44:47]
	v_mfma_f32_16x16x32_bf16 v[40:43], v[176:179], v[200:203], v[40:43]
	v_mfma_f32_16x16x32_bf16 v[28:31], v[162:165], v[208:211], v[28:31]
	v_mfma_f32_16x16x32_bf16 v[24:27], v[176:179], v[208:211], v[24:27]
	v_mfma_f32_16x16x32_bf16 v[12:15], v[162:165], v[216:219], v[12:15]
	v_mfma_f32_16x16x32_bf16 v[8:11], v[176:179], v[216:219], v[8:11]
	s_barrier
	s_add_u32 s14, s58, 0x40000
	s_addc_u32 s15, s59, 0
	s_add_i32 s16, s17, s88
	s_mov_b32 m0, s16
	s_nop 0
	global_load_lds_dwordx4 v128, s[14:15]
	s_add_i32 m0, s16, 0x2000
	s_nop 0
	global_load_lds_dwordx4 v152, s[14:15]
	s_add_i32 vcc_lo, vcc_lo, 2
	s_add_u32 s56, s56, 0x100
	s_addc_u32 s57, s57, 0
	s_add_u32 s76, s76, 0x100
	s_addc_u32 s77, s77, 0
	s_waitcnt vmcnt(6)
	s_barrier
; #define PG8_STAGE(bufoff, gbase, voff) do { _Pragma("unroll") for (int _i = 0; _i < 2; ++_i) \
;         __builtin_amdgcn_global_load_lds((const unsigned*)((const char*)(gbase) + (voff)[_i]), (PG8_LAS unsigned*)(lds + (bufoff) + ldsw + _i * 8192), 16, 0, 0); } while (0)
; #define PG8_LDA(dst, b, h) do { _Pragma("unroll") for (int m = 0; m < 4; ++m) _Pragma("unroll") for (int k = 0; k < 2; ++k) dst[m][k] = *(const PG8_LAS bf16x8*)(lds + PG8_SA(b, h) + aoff + m * 2048 + k * 1024); } while (0)
; #define PG8_LDB(dst, b, h) do { _Pragma("unroll") for (int n = 0; n < 2; ++n) _Pragma("unroll") for (int k = 0; k < 2; ++k) dst[n][k] = *(const PG8_LAS bf16x8*)(lds + PG8_SB(b, h) + boff + n * 2048 + k * 1024); } while (0)
; #define PG8_MMA(ai, bj, At, Bt) do { __builtin_amdgcn_s_setprio(1); _Pragma("unroll") for (int m = 0; m < 4; ++m) _Pragma("unroll") for (int n = 0; n < 2; ++n) _Pragma("unroll") for (int k = 0; k < 2; ++k) \
;         acc[ai][bj][m][n] = __builtin_amdgcn_mfma_f32_16x16x32_bf16(Bt[n][k], At[m][k], acc[ai][bj][m][n], 0, 0, 0); __builtin_amdgcn_s_setprio(0); } while (0)
; #define PG8_WAIT_V(n) asm volatile("s_waitcnt vmcnt(" #n ")" ::: "memory")
; #define PG8_WAIT_L(n) asm volatile("s_waitcnt lgkmcnt(" #n ")" ::: "memory")
; #define PG8_BAR __builtin_amdgcn_s_barrier()
; #define PG8_SCHED __builtin_amdgcn_sched_barrier(0)
; template <class Epi, class Sched, bool STAMP = false>
; __device__ __forceinline__ void gemm_phase(PG8_LAS unsigned char* lds, const Gemm g, const Sched& S, const Epi& E, unsigned long long* stamps) {
;     ...
;             PG8_WAIT_V(6); PG8_BAR; PG8_MMA(1, 1, At, B1); PG8_BAR;
;             PG8_LDB(B0, 1, 0); PG8_SCHED; PG8_LDA(At, 1, 0); PG8_STAGE(PG8_SA(0, 1), a2 + hstep, voffA);
;             PG8_WAIT_L(8); PG8_BAR; PG8_WAIT_L(0); PG8_MMA(0, 0, At, B0); PG8_BAR; PG8_SCHED;
;             PG8_LDB(B1, 1, 1); PG8_STAGE(PG8_SB(1, 0), b3, voffB);
;             PG8_BAR; PG8_WAIT_L(0); PG8_MMA(0, 1, At, B1); PG8_BAR;
;             PG8_LDA(At, 1, 1); PG8_STAGE(PG8_SA(1, 0), a3, voffA);
;             PG8_BAR; PG8_WAIT_L(0); PG8_MMA(1, 0, At, B0); PG8_BAR; PG8_SCHED;
	v_mfma_f32_16x16x32_bf16 v[52:55], v[220:223], v[180:183], v[52:55]
	v_mfma_f32_16x16x32_bf16 v[48:51], v[228:231], v[180:183], v[48:51]
	v_mfma_f32_16x16x32_bf16 v[36:39], v[220:223], v[196:199], v[36:39]
	v_mfma_f32_16x16x32_bf16 v[32:35], v[228:231], v[196:199], v[32:35]
	v_mfma_f32_16x16x32_bf16 v[20:23], v[220:223], v[204:207], v[20:23]
	v_mfma_f32_16x16x32_bf16 v[16:19], v[228:231], v[204:207], v[16:19]
	v_mfma_f32_16x16x32_bf16 v[4:7], v[220:223], v[212:215], v[4:7]
	v_mfma_f32_16x16x32_bf16 v[0:3], v[228:231], v[212:215], v[0:3]
	v_mfma_f32_16x16x32_bf16 v[52:55], v[224:227], v[192:195], v[52:55]
	v_mfma_f32_16x16x32_bf16 v[48:51], v[232:235], v[192:195], v[48:51]
	v_mfma_f32_16x16x32_bf16 v[36:39], v[224:227], v[200:203], v[36:39]
	v_mfma_f32_16x16x32_bf16 v[32:35], v[232:235], v[200:203], v[32:35]
	v_mfma_f32_16x16x32_bf16 v[20:23], v[224:227], v[208:211], v[20:23]
	v_mfma_f32_16x16x32_bf16 v[16:19], v[232:235], v[208:211], v[16:19]
	v_mfma_f32_16x16x32_bf16 v[4:7], v[224:227], v[216:219], v[4:7]
	v_mfma_f32_16x16x32_bf16 v[0:3], v[232:235], v[216:219], v[0:3]
	s_add_i32 s16, 0, 0x18000
	s_barrier
	ds_read_b128 v[158:161], v250
	ds_read_b128 v[162:165], v250 offset:1024
	ds_read_b128 v[172:175], v250 offset:2048
	ds_read_b128 v[176:179], v250 offset:3072
	s_add_u32 s14, s60, 0x40000
	s_addc_u32 s15, s61, 0
	s_mov_b32 m0, s97
	ds_read_b128 v[180:183], v171 offset:32768
	ds_read_b128 v[192:195], v171 offset:33792
	ds_read_b128 v[196:199], v171 offset:34816
	ds_read_b128 v[200:203], v171 offset:35840
	ds_read_b128 v[204:207], v171 offset:36864
	ds_read_b128 v[208:211], v171 offset:37888
	ds_read_b128 v[212:215], v171 offset:38912
	global_load_lds_dwordx4 v148, s[14:15]
	s_mov_b32 m0, s64
	ds_read_b128 v[216:219], v171 offset:39936
	global_load_lds_dwordx4 v150, s[14:15]
	s_waitcnt lgkmcnt(8)
	s_barrier
	s_waitcnt lgkmcnt(0)
	v_mfma_f32_16x16x32_bf16 v[124:127], v[158:161], v[180:183], v[124:127]
	v_mfma_f32_16x16x32_bf16 v[120:123], v[172:175], v[180:183], v[120:123]
	v_mfma_f32_16x16x32_bf16 v[108:111], v[158:161], v[196:199], v[108:111]
	v_mfma_f32_16x16x32_bf16 v[104:107], v[172:175], v[196:199], v[104:107]
	v_mfma_f32_16x16x32_bf16 v[92:95], v[158:161], v[204:207], v[92:95]
	v_mfma_f32_16x16x32_bf16 v[88:91], v[172:175], v[204:207], v[88:91]
	v_mfma_f32_16x16x32_bf16 v[76:79], v[158:161], v[212:215], v[76:79]
	v_mfma_f32_16x16x32_bf16 v[72:75], v[172:175], v[212:215], v[72:75]
	v_mfma_f32_16x16x32_bf16 v[124:127], v[162:165], v[192:195], v[124:127]
	v_mfma_f32_16x16x32_bf16 v[120:123], v[176:179], v[192:195], v[120:123]
	v_mfma_f32_16x16x32_bf16 v[108:111], v[162:165], v[200:203], v[108:111]
	v_mfma_f32_16x16x32_bf16 v[104:107], v[176:179], v[200:203], v[104:107]
	v_mfma_f32_16x16x32_bf16 v[92:95], v[162:165], v[208:211], v[92:95]
	v_mfma_f32_16x16x32_bf16 v[88:91], v[176:179], v[208:211], v[88:91]
	v_mfma_f32_16x16x32_bf16 v[76:79], v[162:165], v[216:219], v[76:79]
	v_mfma_f32_16x16x32_bf16 v[72:75], v[176:179], v[216:219], v[72:75]
	s_barrier
	s_add_i32 s17, 0, 0x1c000
	s_add_i32 s14, s16, s88
	s_mov_b32 m0, s14
	ds_read_b128 v[220:223], v251
	ds_read_b128 v[224:227], v251 offset:1024
	ds_read_b128 v[228:231], v251 offset:2048
	global_load_lds_dwordx4 v244, s[58:59]
	s_add_i32 m0, s14, 0x2000
	ds_read_b128 v[232:235], v251 offset:3072
	global_load_lds_dwordx4 v245, s[58:59]
	s_barrier
	s_waitcnt lgkmcnt(0)
	v_mfma_f32_16x16x32_bf16 v[116:119], v[220:223], v[180:183], v[116:119]
	v_mfma_f32_16x16x32_bf16 v[112:115], v[228:231], v[180:183], v[112:115]
	v_mfma_f32_16x16x32_bf16 v[100:103], v[220:223], v[196:199], v[100:103]
	v_mfma_f32_16x16x32_bf16 v[96:99], v[228:231], v[196:199], v[96:99]
	v_mfma_f32_16x16x32_bf16 v[84:87], v[220:223], v[204:207], v[84:87]
	v_mfma_f32_16x16x32_bf16 v[80:83], v[228:231], v[204:207], v[80:83]
	v_mfma_f32_16x16x32_bf16 v[68:71], v[220:223], v[212:215], v[68:71]
	v_mfma_f32_16x16x32_bf16 v[64:67], v[228:231], v[212:215], v[64:67]
	v_mfma_f32_16x16x32_bf16 v[116:119], v[224:227], v[192:195], v[116:119]
	v_mfma_f32_16x16x32_bf16 v[112:115], v[232:235], v[192:195], v[112:115]
	v_mfma_f32_16x16x32_bf16 v[100:103], v[224:227], v[200:203], v[100:103]
	v_mfma_f32_16x16x32_bf16 v[96:99], v[232:235], v[200:203], v[96:99]
	v_mfma_f32_16x16x32_bf16 v[84:87], v[224:227], v[208:211], v[84:87]
	v_mfma_f32_16x16x32_bf16 v[80:83], v[232:235], v[208:211], v[80:83]
	v_mfma_f32_16x16x32_bf16 v[68:71], v[224:227], v[216:219], v[68:71]
	v_mfma_f32_16x16x32_bf16 v[64:67], v[232:235], v[216:219], v[64:67]
	s_mov_b32 m0, s62
	s_barrier
	ds_read_b128 v[180:183], v171 offset:49152
	ds_read_b128 v[192:195], v171 offset:50176
	ds_read_b128 v[196:199], v171 offset:51200
	ds_read_b128 v[200:203], v171 offset:52224
	ds_read_b128 v[204:207], v171 offset:53248
	ds_read_b128 v[208:211], v171 offset:54272
	ds_read_b128 v[212:215], v171 offset:55296
	global_load_lds_dwordx4 v246, s[60:61]
	s_mov_b32 m0, s63
	ds_read_b128 v[216:219], v171 offset:56320
	global_load_lds_dwordx4 v247, s[60:61]
	s_barrier
	s_waitcnt lgkmcnt(0)
	v_mfma_f32_16x16x32_bf16 v[60:63], v[158:161], v[180:183], v[60:63]
	v_mfma_f32_16x16x32_bf16 v[56:59], v[172:175], v[180:183], v[56:59]
	v_mfma_f32_16x16x32_bf16 v[44:47], v[158:161], v[196:199], v[44:47]
	v_mfma_f32_16x16x32_bf16 v[40:43], v[172:175], v[196:199], v[40:43]
	v_mfma_f32_16x16x32_bf16 v[28:31], v[158:161], v[204:207], v[28:31]
	v_mfma_f32_16x16x32_bf16 v[24:27], v[172:175], v[204:207], v[24:27]
	v_mfma_f32_16x16x32_bf16 v[12:15], v[158:161], v[212:215], v[12:15]
	v_mfma_f32_16x16x32_bf16 v[8:11], v[172:175], v[212:215], v[8:11]
	v_mfma_f32_16x16x32_bf16 v[60:63], v[162:165], v[192:195], v[60:63]
	v_mfma_f32_16x16x32_bf16 v[56:59], v[176:179], v[192:195], v[56:59]
	v_mfma_f32_16x16x32_bf16 v[44:47], v[162:165], v[200:203], v[44:47]
	v_mfma_f32_16x16x32_bf16 v[40:43], v[176:179], v[200:203], v[40:43]
	v_mfma_f32_16x16x32_bf16 v[28:31], v[162:165], v[208:211], v[28:31]
	v_mfma_f32_16x16x32_bf16 v[24:27], v[176:179], v[208:211], v[24:27]
	v_mfma_f32_16x16x32_bf16 v[12:15], v[162:165], v[216:219], v[12:15]
	v_mfma_f32_16x16x32_bf16 v[8:11], v[176:179], v[216:219], v[8:11]
	s_barrier
; __device__ __forceinline__ unsigned cvt_pk_bf16(float lo, float hi) { const f32x2_cv v = {lo, hi}; const bf16x2_cv b = __builtin_convertvector(v, bf16x2_cv); return __builtin_bit_cast(unsigned, b); }
; #define PG8_WAIT_V(n) asm volatile("s_waitcnt vmcnt(" #n ")" ::: "memory")
; #define PG8_BAR __builtin_amdgcn_s_barrier()
; template <class Epi, class Sched, bool STAMP = false>
; __device__ __forceinline__ void gemm_phase(PG8_LAS unsigned char* lds, const Gemm g, const Sched& S, const Epi& E, unsigned long long* stamps) {
;     ...
;             PG8_BAR; PG8_WAIT_L(0); PG8_MMA(1, 0, At, B0); PG8_BAR; PG8_SCHED;
;             PG8_STAGE(PG8_SB(1, 1), b3 + hstep, voffB);
;             PG8_WAIT_V(6); PG8_BAR; PG8_MMA(1, 1, At, B1); PG8_BAR;
;     __device__ __forceinline__ void operator()(const f32x4 (&acc)[2][2][4][2], const pg8::Unit& u, int wr, int wc, int fr, int fq) const {
;         const int row0 = u.pm * 256 + wr * 64 + fr, col0 = u.pn * 256 + wc * 32 + 8 * fq;
; #pragma unroll
;         for (int ai = 0; ai < 2; ++ai)
; #pragma unroll
;             for (int m = 0; m < 4; ++m) {
;                 const int row = row0 + ai * 128 + m * 16;
;                 const float s = rstd_of(rowss, row);
; #pragma unroll
;                 for (int bj = 0; bj < 2; ++bj) {
;                     const size_t off = (size_t)row * 1024 + col0 + bj * 128;
;                     const u32x4 tv = *(const u32x4*)(Tm + off);
;                     u32x4 pv = (u32x4){0u, 0u, 0u, 0u};
;                     if (ACC) pv = *(const u32x4*)(M + off);
;                     const f32x4 a0 = acc[ai][bj][m][0] * s, a1 = acc[ai][bj][m][1] * s;
;                     float o[8];
;                     o[0] = sigm(a0[0]) * lo16(tv.x); o[1] = sigm(a0[1]) * hi16(tv.x); o[2] = sigm(a0[2]) * lo16(tv.y); o[3] = sigm(a0[3]) * hi16(tv.y);
;                     o[4] = sigm(a1[0]) * lo16(tv.z); o[5] = sigm(a1[1]) * hi16(tv.z); o[6] = sigm(a1[2]) * lo16(tv.w); o[7] = sigm(a1[3]) * hi16(tv.w);
;                     if (ACC) { o[0] += lo16(pv.x); o[1] += hi16(pv.x); o[2] += lo16(pv.y); o[3] += hi16(pv.y); o[4] += lo16(pv.z); o[5] += hi16(pv.z); o[6] += lo16(pv.w); o[7] += hi16(pv.w); }
;                     u32x4 w; w.x = cvt_pk_bf16(o[0], o[1]); w.y = cvt_pk_bf16(o[2], o[3]); w.z = cvt_pk_bf16(o[4], o[5]); w.w = cvt_pk_bf16(o[6], o[7]);
;                     *(u32x4*)(M + off) = w; } }
	s_add_u32 s14, s58, 0x40080
	s_addc_u32 s15, s59, 0
	s_add_i32 s16, s17, s88
	s_mov_b32 m0, s16
	s_nop 0
	global_load_lds_dwordx4 v128, s[14:15]
	s_add_i32 m0, s16, 0x2000
	s_nop 0
	global_load_lds_dwordx4 v152, s[14:15]
	s_waitcnt vmcnt(6)
	s_barrier
	v_mfma_f32_16x16x32_bf16 v[52:55], v[220:223], v[180:183], v[52:55]
	v_mfma_f32_16x16x32_bf16 v[48:51], v[228:231], v[180:183], v[48:51]
	v_mfma_f32_16x16x32_bf16 v[36:39], v[220:223], v[196:199], v[36:39]
	v_mfma_f32_16x16x32_bf16 v[32:35], v[228:231], v[196:199], v[32:35]
	v_mfma_f32_16x16x32_bf16 v[20:23], v[220:223], v[204:207], v[20:23]
	v_mfma_f32_16x16x32_bf16 v[16:19], v[228:231], v[204:207], v[16:19]
	v_mfma_f32_16x16x32_bf16 v[4:7], v[220:223], v[212:215], v[4:7]
	v_mfma_f32_16x16x32_bf16 v[0:3], v[228:231], v[212:215], v[0:3]
	v_mfma_f32_16x16x32_bf16 v[52:55], v[224:227], v[192:195], v[52:55]
	v_mfma_f32_16x16x32_bf16 v[48:51], v[232:235], v[192:195], v[48:51]
	v_mfma_f32_16x16x32_bf16 v[36:39], v[224:227], v[200:203], v[36:39]
	v_mfma_f32_16x16x32_bf16 v[32:35], v[232:235], v[200:203], v[32:35]
	v_mfma_f32_16x16x32_bf16 v[20:23], v[224:227], v[208:211], v[20:23]
	v_mfma_f32_16x16x32_bf16 v[16:19], v[232:235], v[208:211], v[16:19]
	v_mfma_f32_16x16x32_bf16 v[4:7], v[224:227], v[216:219], v[4:7]
	v_mfma_f32_16x16x32_bf16 v[0:3], v[232:235], v[216:219], v[0:3]
	s_cmp_gt_u32 vcc_lo, 13
	s_barrier
	s_cbranch_scc0 .LBB0_353
	v_lshl_add_u32 v164, s2, 8, v139
	v_ashrrev_i32_e32 v165, 31, v164
	v_lshl_add_u64 v[160:161], v[164:165], 2, s[40:41]
	global_load_dword v158, v[160:161], off
	v_lshl_or_b32 v162, s3, 8, v170
	v_ashrrev_i32_e32 v163, 31, v162
	s_mov_b64 s[2:3], 0x40000
	s_mov_b64 s[58:59], s[36:37]
	s_mov_b64 s[56:57], s[4:5]
	s_waitcnt vmcnt(0)
	v_fmamk_f32 v158, v158, 0x3a800000, v187
	v_cmp_gt_f32_e32 vcc, s67, v158
	v_mul_f32_e32 v159, 0x4b800000, v158
	s_nop 0
	v_cndmask_b32_e32 v158, v158, v159, vcc
	v_rsq_f32_e32 v158, v158
	s_nop 0
	v_mul_f32_e32 v159, 0x45800000, v158
	v_cndmask_b32_e32 v166, v158, v159, vcc
	v_lshlrev_b64 v[158:159], 10, v[164:165]
	v_lshl_add_u64 v[158:159], v[158:159], 0, v[162:163]
	v_lshlrev_b64 v[158:159], 1, v[158:159]
	v_lshl_add_u64 v[168:169], s[30:31], 0, v[158:159]
	v_mov_b32_e32 v249, v158
	v_mov_b32_e32 v250, v249
	global_load_dwordx4 v[192:195], v250, s[30:31]
	global_load_dwordx4 v[196:199], v250, s[0:1]
	global_load_dwordx4 v[200:203], v250, s[30:31] offset:256
	global_load_dwordx4 v[204:207], v250, s[0:1] offset:256
	v_add_u32_e32 v250, 0x8000, v249
	global_load_dwordx4 v[208:211], v250, s[30:31]
	global_load_dwordx4 v[212:215], v250, s[0:1]
	global_load_dwordx4 v[216:219], v250, s[30:31] offset:256
	global_load_dwordx4 v[220:223], v250, s[0:1] offset:256
	v_add_u32_e32 v250, 0x10000, v249
	global_load_dwordx4 v[224:227], v250, s[30:31]
	global_load_dwordx4 v[228:231], v250, s[0:1]
	global_load_dwordx4 v[232:235], v250, s[30:31] offset:256
	global_load_dwordx4 v[236:239], v250, s[0:1] offset:256
	global_load_dword v240, v[160:161], off offset:64
	global_load_dword v241, v[160:161], off offset:128
	global_load_dword v244, v[160:161], off offset:192
	global_load_dword v245, v[160:161], off offset:512
	global_load_dword v246, v[160:161], off offset:576
	global_load_dword v247, v[160:161], off offset:640
	global_load_dword v248, v[160:161], off offset:704
	v_lshl_add_u64 v[168:169], s[0:1], 0, v[158:159]
	v_pk_mul_f32 v[126:127], v[126:127], v[166:167] op_sel_hi:[1,0]
	v_pk_mul_f32 v[120:121], v[120:121], v[166:167] op_sel_hi:[1,0]
	v_mul_f32_e32 v126, 0xbfb8aa3b, v126
	v_mul_f32_e32 v127, 0xbfb8aa3b, v127
	v_pk_mul_f32 v[124:125], v[124:125], v[166:167] op_sel_hi:[1,0]
	v_pk_mul_f32 v[122:123], v[122:123], v[166:167] op_sel_hi:[1,0]
	v_exp_f32_e32 v126, v126
	v_exp_f32_e32 v127, v127
	v_mul_f32_e32 v120, 0xbfb8aa3b, v120
	v_mul_f32_e32 v121, 0xbfb8aa3b, v121
	v_mul_f32_e32 v124, 0xbfb8aa3b, v124
	v_mul_f32_e32 v125, 0xbfb8aa3b, v125
	v_exp_f32_e32 v120, v120
	v_exp_f32_e32 v121, v121
	v_mul_f32_e32 v122, 0xbfb8aa3b, v122
	v_mul_f32_e32 v123, 0xbfb8aa3b, v123
	v_exp_f32_e32 v124, v124
	v_exp_f32_e32 v125, v125
	v_exp_f32_e32 v122, v122
	v_exp_f32_e32 v123, v123
	v_add_f32_e32 v126, 1.0, v126
	v_add_f32_e32 v127, 1.0, v127
	v_rcp_f32_e32 v126, v126
	v_rcp_f32_e32 v127, v127
	v_add_f32_e32 v120, 1.0, v120
	v_add_f32_e32 v121, 1.0, v121
	v_add_f32_e32 v124, 1.0, v124
	v_add_f32_e32 v125, 1.0, v125
	v_rcp_f32_e32 v120, v120
	v_rcp_f32_e32 v121, v121
	v_add_f32_e32 v122, 1.0, v122
	v_add_f32_e32 v123, 1.0, v123
	v_rcp_f32_e32 v124, v124
	v_rcp_f32_e32 v125, v125
	v_rcp_f32_e32 v122, v122
	v_rcp_f32_e32 v123, v123
	v_pk_mul_f32 v[116:117], v[116:117], v[166:167] op_sel_hi:[1,0]
	v_pk_mul_f32 v[114:115], v[114:115], v[166:167] op_sel_hi:[1,0]
	s_waitcnt vmcnt(0)
; __device__ __forceinline__ unsigned cvt_pk_bf16(float lo, float hi) { const f32x2_cv v = {lo, hi}; const bf16x2_cv b = __builtin_convertvector(v, bf16x2_cv); return __builtin_bit_cast(unsigned, b); }
; __device__ __forceinline__ float sigm(float x) { return __builtin_amdgcn_rcpf(1.0f + __expf(-x)); }
; __device__ __forceinline__ float lo16(unsigned w) { return __uint_as_float(w << 16); }
; __device__ __forceinline__ float hi16(unsigned w) { return __uint_as_float(w & 0xffff0000u); }
; __device__ __forceinline__ float rstd_of(const float* rowss, int row) { return rsqrtf(rowss[row] * (1.0f / 1024.0f) + 1e-6f); }
;     __device__ __forceinline__ void operator()(const f32x4 (&acc)[2][2][4][2], const pg8::Unit& u, int wr, int wc, int fr, int fq) const {
;         const int row0 = u.pm * 256 + wr * 64 + fr, col0 = u.pn * 256 + wc * 32 + 8 * fq;
; #pragma unroll
;         for (int ai = 0; ai < 2; ++ai)
; #pragma unroll
;             for (int m = 0; m < 4; ++m) {
;                 const int row = row0 + ai * 128 + m * 16;
;                 const float s = rstd_of(rowss, row);
; #pragma unroll
;                 for (int bj = 0; bj < 2; ++bj) {
;                     const size_t off = (size_t)row * 1024 + col0 + bj * 128;
;                     const u32x4 tv = *(const u32x4*)(Tm + off);
;                     u32x4 pv = (u32x4){0u, 0u, 0u, 0u};
;                     if (ACC) pv = *(const u32x4*)(M + off);
;                     const f32x4 a0 = acc[ai][bj][m][0] * s, a1 = acc[ai][bj][m][1] * s;
;                     float o[8];
;                     o[0] = sigm(a0[0]) * lo16(tv.x); o[1] = sigm(a0[1]) * hi16(tv.x); o[2] = sigm(a0[2]) * lo16(tv.y); o[3] = sigm(a0[3]) * hi16(tv.y);
;                     o[4] = sigm(a1[0]) * lo16(tv.z); o[5] = sigm(a1[1]) * hi16(tv.z); o[6] = sigm(a1[2]) * lo16(tv.w); o[7] = sigm(a1[3]) * hi16(tv.w);
;                     if (ACC) { o[0] += lo16(pv.x); o[1] += hi16(pv.x); o[2] += lo16(pv.y); o[3] += hi16(pv.y); o[4] += lo16(pv.z); o[5] += hi16(pv.z); o[6] += lo16(pv.w); o[7] += hi16(pv.w); }
;                     u32x4 w; w.x = cvt_pk_bf16(o[0], o[1]); w.y = cvt_pk_bf16(o[2], o[3]); w.z = cvt_pk_bf16(o[4], o[5]); w.w = cvt_pk_bf16(o[6], o[7]);
;                     *(u32x4*)(M + off) = w; } }
	v_mov_b32_e32 v172, v192
	v_mov_b32_e32 v173, v193
	v_mov_b32_e32 v174, v194
	v_mov_b32_e32 v175, v195
	v_mov_b32_e32 v176, v196
	v_mov_b32_e32 v177, v197
	v_mov_b32_e32 v178, v198
	v_mov_b32_e32 v179, v199
	v_lshlrev_b32_e32 v180, 16, v172
	v_and_b32_e32 v181, 0xffff0000, v172
	v_lshlrev_b32_e32 v182, 16, v176
	v_and_b32_e32 v183, 0xffff0000, v176
	v_lshlrev_b32_e32 v172, 16, v173
	v_and_b32_e32 v173, 0xffff0000, v173
	v_lshlrev_b32_e32 v176, 16, v177
	v_and_b32_e32 v177, 0xffff0000, v177
	v_pk_fma_f32 v[126:127], v[126:127], v[172:173], v[176:177]
	v_lshlrev_b32_e32 v172, 16, v174
	v_and_b32_e32 v173, 0xffff0000, v174
	v_lshlrev_b32_e32 v176, 16, v178
	v_and_b32_e32 v177, 0xffff0000, v178
	v_pk_fma_f32 v[172:173], v[120:121], v[172:173], v[176:177]
	v_lshlrev_b32_e32 v120, 16, v175
	v_and_b32_e32 v121, 0xffff0000, v175
	v_lshlrev_b32_e32 v174, 16, v179
	v_and_b32_e32 v175, 0xffff0000, v179
	v_pk_fma_f32 v[124:125], v[124:125], v[180:181], v[182:183]
	v_pk_fma_f32 v[174:175], v[122:123], v[120:121], v[174:175]
	v_cvt_pk_bf16_f32 v120, v124, v125
	v_cvt_pk_bf16_f32 v121, v126, v127
	v_cvt_pk_bf16_f32 v122, v172, v173
	v_cvt_pk_bf16_f32 v123, v174, v175
	v_or_b32_e32 v124, 0x100, v158
	v_mov_b32_e32 v125, v159
	global_store_dwordx4 v[168:169], v[120:123], off
	v_lshl_add_u64 v[168:169], s[0:1], 0, v[124:125]
	v_pk_mul_f32 v[172:173], v[118:119], v[166:167] op_sel_hi:[1,0]
	v_lshl_add_u64 v[120:121], s[30:31], 0, v[124:125]
	s_nop 1
	v_mov_b32_e32 v120, v200
	v_mov_b32_e32 v121, v201
	v_mov_b32_e32 v122, v202
	v_mov_b32_e32 v123, v203
	v_pk_mul_f32 v[118:119], v[112:113], v[166:167] op_sel_hi:[1,0]
	s_nop 1
	v_mov_b32_e32 v124, v204
	v_mov_b32_e32 v125, v205
	v_mov_b32_e32 v126, v206
	v_mov_b32_e32 v127, v207
	v_add_u32_e32 v250, 0x18000, v249
	global_load_dwordx4 v[192:195], v250, s[30:31]
	global_load_dwordx4 v[196:199], v250, s[0:1]
	global_load_dwordx4 v[200:203], v250, s[30:31] offset:256
	global_load_dwordx4 v[204:207], v250, s[0:1] offset:256
	v_mul_f32_e32 v112, 0xbfb8aa3b, v116
	v_mul_f32_e32 v113, 0xbfb8aa3b, v117
	v_mul_f32_e32 v116, 0xbfb8aa3b, v172
	v_mul_f32_e32 v117, 0xbfb8aa3b, v173
	v_exp_f32_e32 v116, v116
	v_exp_f32_e32 v117, v117
	v_mul_f32_e32 v118, 0xbfb8aa3b, v118
	v_mul_f32_e32 v119, 0xbfb8aa3b, v119
	v_exp_f32_e32 v118, v118
	v_exp_f32_e32 v119, v119
	v_mul_f32_e32 v114, 0xbfb8aa3b, v114
	v_mul_f32_e32 v115, 0xbfb8aa3b, v115
	v_exp_f32_e32 v112, v112
	v_exp_f32_e32 v113, v113
	v_exp_f32_e32 v114, v114
	v_exp_f32_e32 v115, v115
	v_add_f32_e32 v116, 1.0, v116
	v_add_f32_e32 v117, 1.0, v117
	v_rcp_f32_e32 v116, v116
	v_rcp_f32_e32 v117, v117
	v_add_f32_e32 v118, 1.0, v118
	v_add_f32_e32 v119, 1.0, v119
	v_add_f32_e32 v112, 1.0, v112
	v_add_f32_e32 v113, 1.0, v113
	v_rcp_f32_e32 v118, v118
	v_rcp_f32_e32 v119, v119
	v_add_f32_e32 v114, 1.0, v114
	v_add_f32_e32 v115, 1.0, v115
	v_rcp_f32_e32 v112, v112
	v_rcp_f32_e32 v113, v113
	v_rcp_f32_e32 v114, v114
	v_rcp_f32_e32 v115, v115
	v_lshlrev_b32_e32 v172, 16, v120
	v_and_b32_e32 v173, 0xffff0000, v120
	v_lshlrev_b32_e32 v174, 16, v124
	v_and_b32_e32 v175, 0xffff0000, v124
	v_lshlrev_b32_e32 v120, 16, v121
	v_and_b32_e32 v121, 0xffff0000, v121
	v_lshlrev_b32_e32 v124, 16, v125
	v_and_b32_e32 v125, 0xffff0000, v125
	v_pk_fma_f32 v[116:117], v[116:117], v[120:121], v[124:125]
	v_lshlrev_b32_e32 v120, 16, v122
	v_and_b32_e32 v121, 0xffff0000, v122
	v_lshlrev_b32_e32 v124, 16, v126
	v_and_b32_e32 v125, 0xffff0000, v126
	v_pk_fma_f32 v[118:119], v[118:119], v[120:121], v[124:125]
	v_lshlrev_b32_e32 v120, 16, v123
	v_and_b32_e32 v121, 0xffff0000, v123
	v_lshlrev_b32_e32 v122, 16, v127
	v_and_b32_e32 v123, 0xffff0000, v127
	v_pk_fma_f32 v[112:113], v[112:113], v[172:173], v[174:175]
	v_pk_fma_f32 v[120:121], v[114:115], v[120:121], v[122:123]
	v_cvt_pk_bf16_f32 v112, v112, v113
	v_cvt_pk_bf16_f32 v113, v116, v117
	v_cvt_pk_bf16_f32 v114, v118, v119
	v_cvt_pk_bf16_f32 v115, v120, v121
	global_store_dwordx4 v[168:169], v[112:115], off
	s_nop 1
	v_mov_b32_e32 v112, v240
	s_nop 0
	v_or_b32_e32 v114, 16, v164
	v_ashrrev_i32_e32 v115, 31, v114
	v_lshlrev_b64 v[114:115], 10, v[114:115]
	v_lshl_add_u64 v[114:115], v[114:115], 0, v[162:163]
	v_lshlrev_b64 v[114:115], 1, v[114:115]
	v_lshl_add_u64 v[116:117], s[30:31], 0, v[114:115]
	v_lshl_add_u64 v[124:125], s[0:1], 0, v[114:115]
	s_nop 1
	v_mov_b32_e32 v116, v208
	v_mov_b32_e32 v117, v209
	v_mov_b32_e32 v118, v210
	v_mov_b32_e32 v119, v211
	v_or_b32_e32 v114, 0x100, v114
	s_nop 1
	v_mov_b32_e32 v120, v212
	v_mov_b32_e32 v121, v213
	v_mov_b32_e32 v122, v214
	v_mov_b32_e32 v123, v215
	v_fmamk_f32 v112, v112, 0x3a800000, v187
	v_cmp_gt_f32_e32 vcc, s67, v112
	v_mul_f32_e32 v113, 0x4b800000, v112
	v_lshlrev_b32_e32 v126, 16, v116
	v_cndmask_b32_e32 v112, v112, v113, vcc
	v_rsq_f32_e32 v112, v112
	v_and_b32_e32 v127, 0xffff0000, v116
	v_lshlrev_b32_e32 v168, 16, v120
	v_and_b32_e32 v169, 0xffff0000, v120
	v_mul_f32_e32 v113, 0x45800000, v112
	v_cndmask_b32_e32 v112, v112, v113, vcc
	v_pk_mul_f32 v[110:111], v[110:111], v[112:113] op_sel_hi:[1,0]
	v_pk_mul_f32 v[104:105], v[104:105], v[112:113] op_sel_hi:[1,0]
	v_mul_f32_e32 v110, 0xbfb8aa3b, v110
	v_mul_f32_e32 v111, 0xbfb8aa3b, v111
	v_pk_mul_f32 v[108:109], v[108:109], v[112:113] op_sel_hi:[1,0]
	v_pk_mul_f32 v[106:107], v[106:107], v[112:113] op_sel_hi:[1,0]
	v_exp_f32_e32 v110, v110
	v_exp_f32_e32 v111, v111
	v_mul_f32_e32 v104, 0xbfb8aa3b, v104
	v_mul_f32_e32 v105, 0xbfb8aa3b, v105
	v_mul_f32_e32 v108, 0xbfb8aa3b, v108
	v_mul_f32_e32 v109, 0xbfb8aa3b, v109
	v_exp_f32_e32 v104, v104
	v_exp_f32_e32 v105, v105
	v_mul_f32_e32 v106, 0xbfb8aa3b, v106
	v_mul_f32_e32 v107, 0xbfb8aa3b, v107
; __device__ __forceinline__ unsigned cvt_pk_bf16(float lo, float hi) { const f32x2_cv v = {lo, hi}; const bf16x2_cv b = __builtin_convertvector(v, bf16x2_cv); return __builtin_bit_cast(unsigned, b); }
; __device__ __forceinline__ float sigm(float x) { return __builtin_amdgcn_rcpf(1.0f + __expf(-x)); }
; __device__ __forceinline__ float lo16(unsigned w) { return __uint_as_float(w << 16); }
; __device__ __forceinline__ float hi16(unsigned w) { return __uint_as_float(w & 0xffff0000u); }
; __device__ __forceinline__ float rstd_of(const float* rowss, int row) { return rsqrtf(rowss[row] * (1.0f / 1024.0f) + 1e-6f); }
;     __device__ __forceinline__ void operator()(const f32x4 (&acc)[2][2][4][2], const pg8::Unit& u, int wr, int wc, int fr, int fq) const {
;         const int row0 = u.pm * 256 + wr * 64 + fr, col0 = u.pn * 256 + wc * 32 + 8 * fq;
; #pragma unroll
;         for (int ai = 0; ai < 2; ++ai)
; #pragma unroll
;             for (int m = 0; m < 4; ++m) {
;                 const int row = row0 + ai * 128 + m * 16;
;                 const float s = rstd_of(rowss, row);
; #pragma unroll
;                 for (int bj = 0; bj < 2; ++bj) {
;                     const size_t off = (size_t)row * 1024 + col0 + bj * 128;
;                     const u32x4 tv = *(const u32x4*)(Tm + off);
;                     u32x4 pv = (u32x4){0u, 0u, 0u, 0u};
;                     if (ACC) pv = *(const u32x4*)(M + off);
;                     const f32x4 a0 = acc[ai][bj][m][0] * s, a1 = acc[ai][bj][m][1] * s;
;                     float o[8];
;                     o[0] = sigm(a0[0]) * lo16(tv.x); o[1] = sigm(a0[1]) * hi16(tv.x); o[2] = sigm(a0[2]) * lo16(tv.y); o[3] = sigm(a0[3]) * hi16(tv.y);
;                     o[4] = sigm(a1[0]) * lo16(tv.z); o[5] = sigm(a1[1]) * hi16(tv.z); o[6] = sigm(a1[2]) * lo16(tv.w); o[7] = sigm(a1[3]) * hi16(tv.w);
;                     if (ACC) { o[0] += lo16(pv.x); o[1] += hi16(pv.x); o[2] += lo16(pv.y); o[3] += hi16(pv.y); o[4] += lo16(pv.z); o[5] += hi16(pv.z); o[6] += lo16(pv.w); o[7] += hi16(pv.w); }
;                     u32x4 w; w.x = cvt_pk_bf16(o[0], o[1]); w.y = cvt_pk_bf16(o[2], o[3]); w.z = cvt_pk_bf16(o[4], o[5]); w.w = cvt_pk_bf16(o[6], o[7]);
;                     *(u32x4*)(M + off) = w; } }
	v_exp_f32_e32 v108, v108
	v_exp_f32_e32 v109, v109
	v_exp_f32_e32 v106, v106
	v_exp_f32_e32 v107, v107
	v_add_f32_e32 v110, 1.0, v110
	v_add_f32_e32 v111, 1.0, v111
	v_rcp_f32_e32 v110, v110
	v_rcp_f32_e32 v111, v111
	v_add_f32_e32 v104, 1.0, v104
	v_add_f32_e32 v105, 1.0, v105
	v_add_f32_e32 v108, 1.0, v108
	v_add_f32_e32 v109, 1.0, v109
	v_rcp_f32_e32 v104, v104
	v_rcp_f32_e32 v105, v105
	v_add_f32_e32 v106, 1.0, v106
	v_add_f32_e32 v107, 1.0, v107
	v_rcp_f32_e32 v108, v108
	v_rcp_f32_e32 v109, v109
	v_rcp_f32_e32 v106, v106
	v_rcp_f32_e32 v107, v107
	v_lshlrev_b32_e32 v116, 16, v117
	v_and_b32_e32 v117, 0xffff0000, v117
	v_lshlrev_b32_e32 v120, 16, v121
	v_and_b32_e32 v121, 0xffff0000, v121
	v_pk_fma_f32 v[110:111], v[110:111], v[116:117], v[120:121]
	v_lshlrev_b32_e32 v116, 16, v118
	v_and_b32_e32 v117, 0xffff0000, v118
	v_lshlrev_b32_e32 v120, 16, v122
	v_and_b32_e32 v121, 0xffff0000, v122
	v_pk_fma_f32 v[116:117], v[104:105], v[116:117], v[120:121]
	v_lshlrev_b32_e32 v104, 16, v119
	v_and_b32_e32 v105, 0xffff0000, v119
	v_lshlrev_b32_e32 v118, 16, v123
	v_and_b32_e32 v119, 0xffff0000, v123
	v_pk_fma_f32 v[108:109], v[108:109], v[126:127], v[168:169]
	v_pk_fma_f32 v[118:119], v[106:107], v[104:105], v[118:119]
	v_cvt_pk_bf16_f32 v104, v108, v109
	v_cvt_pk_bf16_f32 v105, v110, v111
	v_cvt_pk_bf16_f32 v106, v116, v117
	v_cvt_pk_bf16_f32 v107, v118, v119
	global_store_dwordx4 v[124:125], v[104:107], off
	v_pk_mul_f32 v[102:103], v[102:103], v[112:113] op_sel_hi:[1,0]
	v_pk_mul_f32 v[96:97], v[96:97], v[112:113] op_sel_hi:[1,0]
	v_lshl_add_u64 v[104:105], s[30:31], 0, v[114:115]
	v_lshl_add_u64 v[114:115], s[0:1], 0, v[114:115]
	s_nop 1
	v_mov_b32_e32 v104, v216
	v_mov_b32_e32 v105, v217
	v_mov_b32_e32 v106, v218
	v_mov_b32_e32 v107, v219
	v_mul_f32_e32 v102, 0xbfb8aa3b, v102
	s_nop 1
	v_mov_b32_e32 v108, v220
	v_mov_b32_e32 v109, v221
	v_mov_b32_e32 v110, v222
	v_mov_b32_e32 v111, v223
	v_add_u32_e32 v250, 0x40000, v249
	global_load_dwordx4 v[208:211], v250, s[30:31]
	global_load_dwordx4 v[212:215], v250, s[0:1]
	global_load_dwordx4 v[216:219], v250, s[30:31] offset:256
	global_load_dwordx4 v[220:223], v250, s[0:1] offset:256
	v_mul_f32_e32 v103, 0xbfb8aa3b, v103
	v_pk_mul_f32 v[100:101], v[100:101], v[112:113] op_sel_hi:[1,0]
	v_pk_mul_f32 v[98:99], v[98:99], v[112:113] op_sel_hi:[1,0]
	v_exp_f32_e32 v102, v102
	v_exp_f32_e32 v103, v103
	v_mul_f32_e32 v96, 0xbfb8aa3b, v96
	v_mul_f32_e32 v97, 0xbfb8aa3b, v97
	v_mul_f32_e32 v100, 0xbfb8aa3b, v100
	v_mul_f32_e32 v101, 0xbfb8aa3b, v101
	v_exp_f32_e32 v96, v96
	v_exp_f32_e32 v97, v97
	v_mul_f32_e32 v98, 0xbfb8aa3b, v98
	v_mul_f32_e32 v99, 0xbfb8aa3b, v99
	v_exp_f32_e32 v100, v100
	v_exp_f32_e32 v101, v101
	v_exp_f32_e32 v98, v98
	v_exp_f32_e32 v99, v99
	v_add_f32_e32 v102, 1.0, v102
	v_add_f32_e32 v103, 1.0, v103
	v_rcp_f32_e32 v102, v102
	v_rcp_f32_e32 v103, v103
	v_add_f32_e32 v96, 1.0, v96
	v_add_f32_e32 v97, 1.0, v97
	v_add_f32_e32 v100, 1.0, v100
	v_add_f32_e32 v101, 1.0, v101
	v_rcp_f32_e32 v96, v96
	v_rcp_f32_e32 v97, v97
	v_add_f32_e32 v98, 1.0, v98
	v_add_f32_e32 v99, 1.0, v99
	v_rcp_f32_e32 v100, v100
	v_rcp_f32_e32 v101, v101
	v_rcp_f32_e32 v98, v98
	v_rcp_f32_e32 v99, v99
	v_lshlrev_b32_e32 v112, 16, v104
	v_and_b32_e32 v113, 0xffff0000, v104
	v_lshlrev_b32_e32 v116, 16, v108
	v_and_b32_e32 v117, 0xffff0000, v108
	v_lshlrev_b32_e32 v104, 16, v105
	v_and_b32_e32 v105, 0xffff0000, v105
	v_lshlrev_b32_e32 v108, 16, v109
	v_and_b32_e32 v109, 0xffff0000, v109
	v_pk_fma_f32 v[102:103], v[102:103], v[104:105], v[108:109]
	v_lshlrev_b32_e32 v104, 16, v106
	v_and_b32_e32 v105, 0xffff0000, v106
	v_lshlrev_b32_e32 v108, 16, v110
	v_and_b32_e32 v109, 0xffff0000, v110
	v_pk_fma_f32 v[104:105], v[96:97], v[104:105], v[108:109]
	v_lshlrev_b32_e32 v96, 16, v107
	v_and_b32_e32 v97, 0xffff0000, v107
	v_lshlrev_b32_e32 v106, 16, v111
	v_and_b32_e32 v107, 0xffff0000, v111
	v_pk_fma_f32 v[100:101], v[100:101], v[112:113], v[116:117]
	v_pk_fma_f32 v[106:107], v[98:99], v[96:97], v[106:107]
	v_cvt_pk_bf16_f32 v96, v100, v101
	v_cvt_pk_bf16_f32 v97, v102, v103
	v_cvt_pk_bf16_f32 v98, v104, v105
	v_cvt_pk_bf16_f32 v99, v106, v107
	global_store_dwordx4 v[114:115], v[96:99], off
	s_nop 1
	v_mov_b32_e32 v96, v241
	s_nop 0
	v_or_b32_e32 v98, 32, v164
	v_ashrrev_i32_e32 v99, 31, v98
	v_lshlrev_b64 v[98:99], 10, v[98:99]
	v_lshl_add_u64 v[98:99], v[98:99], 0, v[162:163]
	v_lshlrev_b64 v[98:99], 1, v[98:99]
	v_lshl_add_u64 v[100:101], s[30:31], 0, v[98:99]
	v_lshl_add_u64 v[108:109], s[0:1], 0, v[98:99]
	s_nop 1
	v_mov_b32_e32 v100, v224
	v_mov_b32_e32 v101, v225
	v_mov_b32_e32 v102, v226
	v_mov_b32_e32 v103, v227
	v_or_b32_e32 v98, 0x100, v98
	s_nop 1
	v_mov_b32_e32 v104, v228
	v_mov_b32_e32 v105, v229
	v_mov_b32_e32 v106, v230
	v_mov_b32_e32 v107, v231
	v_fmamk_f32 v96, v96, 0x3a800000, v187
	v_cmp_gt_f32_e32 vcc, s67, v96
	v_mul_f32_e32 v97, 0x4b800000, v96
	v_lshlrev_b32_e32 v110, 16, v100
	v_cndmask_b32_e32 v96, v96, v97, vcc
	v_rsq_f32_e32 v96, v96
	v_and_b32_e32 v111, 0xffff0000, v100
	v_lshlrev_b32_e32 v112, 16, v104
	v_and_b32_e32 v113, 0xffff0000, v104
	v_mul_f32_e32 v97, 0x45800000, v96
	v_cndmask_b32_e32 v96, v96, v97, vcc
	v_pk_mul_f32 v[94:95], v[94:95], v[96:97] op_sel_hi:[1,0]
	v_pk_mul_f32 v[88:89], v[88:89], v[96:97] op_sel_hi:[1,0]
	v_mul_f32_e32 v94, 0xbfb8aa3b, v94
	v_mul_f32_e32 v95, 0xbfb8aa3b, v95
	v_pk_mul_f32 v[92:93], v[92:93], v[96:97] op_sel_hi:[1,0]
	v_pk_mul_f32 v[90:91], v[90:91], v[96:97] op_sel_hi:[1,0]
	v_exp_f32_e32 v94, v94
	v_exp_f32_e32 v95, v95
	v_mul_f32_e32 v88, 0xbfb8aa3b, v88
	v_mul_f32_e32 v89, 0xbfb8aa3b, v89
	v_mul_f32_e32 v92, 0xbfb8aa3b, v92
; __device__ __forceinline__ unsigned cvt_pk_bf16(float lo, float hi) { const f32x2_cv v = {lo, hi}; const bf16x2_cv b = __builtin_convertvector(v, bf16x2_cv); return __builtin_bit_cast(unsigned, b); }
; __device__ __forceinline__ float sigm(float x) { return __builtin_amdgcn_rcpf(1.0f + __expf(-x)); }
; __device__ __forceinline__ float lo16(unsigned w) { return __uint_as_float(w << 16); }
; __device__ __forceinline__ float hi16(unsigned w) { return __uint_as_float(w & 0xffff0000u); }
; __device__ __forceinline__ float rstd_of(const float* rowss, int row) { return rsqrtf(rowss[row] * (1.0f / 1024.0f) + 1e-6f); }
;     __device__ __forceinline__ void operator()(const f32x4 (&acc)[2][2][4][2], const pg8::Unit& u, int wr, int wc, int fr, int fq) const {
;         const int row0 = u.pm * 256 + wr * 64 + fr, col0 = u.pn * 256 + wc * 32 + 8 * fq;
; #pragma unroll
;         for (int ai = 0; ai < 2; ++ai)
; #pragma unroll
;             for (int m = 0; m < 4; ++m) {
;                 const int row = row0 + ai * 128 + m * 16;
;                 const float s = rstd_of(rowss, row);
; #pragma unroll
;                 for (int bj = 0; bj < 2; ++bj) {
;                     const size_t off = (size_t)row * 1024 + col0 + bj * 128;
;                     const u32x4 tv = *(const u32x4*)(Tm + off);
;                     u32x4 pv = (u32x4){0u, 0u, 0u, 0u};
;                     if (ACC) pv = *(const u32x4*)(M + off);
;                     const f32x4 a0 = acc[ai][bj][m][0] * s, a1 = acc[ai][bj][m][1] * s;
;                     float o[8];
;                     o[0] = sigm(a0[0]) * lo16(tv.x); o[1] = sigm(a0[1]) * hi16(tv.x); o[2] = sigm(a0[2]) * lo16(tv.y); o[3] = sigm(a0[3]) * hi16(tv.y);
;                     o[4] = sigm(a1[0]) * lo16(tv.z); o[5] = sigm(a1[1]) * hi16(tv.z); o[6] = sigm(a1[2]) * lo16(tv.w); o[7] = sigm(a1[3]) * hi16(tv.w);
;                     if (ACC) { o[0] += lo16(pv.x); o[1] += hi16(pv.x); o[2] += lo16(pv.y); o[3] += hi16(pv.y); o[4] += lo16(pv.z); o[5] += hi16(pv.z); o[6] += lo16(pv.w); o[7] += hi16(pv.w); }
;                     u32x4 w; w.x = cvt_pk_bf16(o[0], o[1]); w.y = cvt_pk_bf16(o[2], o[3]); w.z = cvt_pk_bf16(o[4], o[5]); w.w = cvt_pk_bf16(o[6], o[7]);
;                     *(u32x4*)(M + off) = w; } }
	v_mul_f32_e32 v93, 0xbfb8aa3b, v93
	v_exp_f32_e32 v88, v88
	v_exp_f32_e32 v89, v89
	v_mul_f32_e32 v90, 0xbfb8aa3b, v90
	v_mul_f32_e32 v91, 0xbfb8aa3b, v91
	v_exp_f32_e32 v92, v92
	v_exp_f32_e32 v93, v93
	v_exp_f32_e32 v90, v90
	v_exp_f32_e32 v91, v91
	v_add_f32_e32 v94, 1.0, v94
	v_add_f32_e32 v95, 1.0, v95
	v_rcp_f32_e32 v94, v94
	v_rcp_f32_e32 v95, v95
	v_add_f32_e32 v88, 1.0, v88
	v_add_f32_e32 v89, 1.0, v89
	v_add_f32_e32 v92, 1.0, v92
	v_add_f32_e32 v93, 1.0, v93
	v_rcp_f32_e32 v88, v88
	v_rcp_f32_e32 v89, v89
	v_add_f32_e32 v90, 1.0, v90
	v_add_f32_e32 v91, 1.0, v91
	v_rcp_f32_e32 v92, v92
	v_rcp_f32_e32 v93, v93
	v_rcp_f32_e32 v90, v90
	v_rcp_f32_e32 v91, v91
	v_lshlrev_b32_e32 v100, 16, v101
	v_and_b32_e32 v101, 0xffff0000, v101
	v_lshlrev_b32_e32 v104, 16, v105
	v_and_b32_e32 v105, 0xffff0000, v105
	v_pk_fma_f32 v[94:95], v[94:95], v[100:101], v[104:105]
	v_lshlrev_b32_e32 v100, 16, v102
	v_and_b32_e32 v101, 0xffff0000, v102
	v_lshlrev_b32_e32 v104, 16, v106
	v_and_b32_e32 v105, 0xffff0000, v106
	v_pk_fma_f32 v[100:101], v[88:89], v[100:101], v[104:105]
	v_lshlrev_b32_e32 v88, 16, v103
	v_and_b32_e32 v89, 0xffff0000, v103
	v_lshlrev_b32_e32 v102, 16, v107
	v_and_b32_e32 v103, 0xffff0000, v107
	v_pk_fma_f32 v[92:93], v[92:93], v[110:111], v[112:113]
	v_pk_fma_f32 v[102:103], v[90:91], v[88:89], v[102:103]
	v_cvt_pk_bf16_f32 v88, v92, v93
	v_cvt_pk_bf16_f32 v89, v94, v95
	v_cvt_pk_bf16_f32 v90, v100, v101
	v_cvt_pk_bf16_f32 v91, v102, v103
	global_store_dwordx4 v[108:109], v[88:91], off
	v_pk_mul_f32 v[86:87], v[86:87], v[96:97] op_sel_hi:[1,0]
	v_pk_mul_f32 v[80:81], v[80:81], v[96:97] op_sel_hi:[1,0]
	v_lshl_add_u64 v[88:89], s[30:31], 0, v[98:99]
	v_lshl_add_u64 v[98:99], s[0:1], 0, v[98:99]
	s_nop 1
	v_mov_b32_e32 v92, v232
	v_mov_b32_e32 v93, v233
	v_mov_b32_e32 v94, v234
	v_mov_b32_e32 v95, v235
	v_mul_f32_e32 v86, 0xbfb8aa3b, v86
	s_nop 1
	v_mov_b32_e32 v88, v236
	v_mov_b32_e32 v89, v237
	v_mov_b32_e32 v90, v238
	v_mov_b32_e32 v91, v239
	v_add_u32_e32 v250, 0x48000, v249
	global_load_dwordx4 v[224:227], v250, s[30:31]
	global_load_dwordx4 v[228:231], v250, s[0:1]
	global_load_dwordx4 v[232:235], v250, s[30:31] offset:256
	global_load_dwordx4 v[236:239], v250, s[0:1] offset:256
	v_mul_f32_e32 v87, 0xbfb8aa3b, v87
	v_pk_mul_f32 v[84:85], v[84:85], v[96:97] op_sel_hi:[1,0]
	v_pk_mul_f32 v[82:83], v[82:83], v[96:97] op_sel_hi:[1,0]
	v_exp_f32_e32 v86, v86
	v_exp_f32_e32 v87, v87
	v_mul_f32_e32 v80, 0xbfb8aa3b, v80
	v_mul_f32_e32 v81, 0xbfb8aa3b, v81
	v_mul_f32_e32 v84, 0xbfb8aa3b, v84
	v_mul_f32_e32 v85, 0xbfb8aa3b, v85
	v_exp_f32_e32 v80, v80
	v_exp_f32_e32 v81, v81
	v_mul_f32_e32 v82, 0xbfb8aa3b, v82
	v_mul_f32_e32 v83, 0xbfb8aa3b, v83
	v_exp_f32_e32 v84, v84
	v_exp_f32_e32 v85, v85
	v_exp_f32_e32 v82, v82
	v_exp_f32_e32 v83, v83
	v_add_f32_e32 v86, 1.0, v86
	v_add_f32_e32 v87, 1.0, v87
	v_rcp_f32_e32 v86, v86
	v_rcp_f32_e32 v87, v87
	v_add_f32_e32 v80, 1.0, v80
	v_add_f32_e32 v81, 1.0, v81
	v_add_f32_e32 v84, 1.0, v84
	v_add_f32_e32 v85, 1.0, v85
	v_rcp_f32_e32 v80, v80
	v_rcp_f32_e32 v81, v81
	v_add_f32_e32 v82, 1.0, v82
	v_add_f32_e32 v83, 1.0, v83
	v_rcp_f32_e32 v84, v84
	v_rcp_f32_e32 v85, v85
	v_rcp_f32_e32 v82, v82
	v_rcp_f32_e32 v83, v83
	v_lshlrev_b32_e32 v96, 16, v92
	v_and_b32_e32 v97, 0xffff0000, v92
	v_lshlrev_b32_e32 v100, 16, v88
	v_and_b32_e32 v101, 0xffff0000, v88
	v_lshlrev_b32_e32 v92, 16, v93
	v_and_b32_e32 v93, 0xffff0000, v93
	v_lshlrev_b32_e32 v88, 16, v89
	v_and_b32_e32 v89, 0xffff0000, v89
	v_pk_fma_f32 v[86:87], v[86:87], v[92:93], v[88:89]
	v_lshlrev_b32_e32 v88, 16, v94
	v_and_b32_e32 v89, 0xffff0000, v94
	v_lshlrev_b32_e32 v92, 16, v90
	v_and_b32_e32 v93, 0xffff0000, v90
	v_pk_fma_f32 v[88:89], v[80:81], v[88:89], v[92:93]
	v_lshlrev_b32_e32 v80, 16, v95
	v_and_b32_e32 v81, 0xffff0000, v95
	v_lshlrev_b32_e32 v90, 16, v91
	v_and_b32_e32 v91, 0xffff0000, v91
	v_pk_fma_f32 v[84:85], v[84:85], v[96:97], v[100:101]
	v_pk_fma_f32 v[90:91], v[82:83], v[80:81], v[90:91]
	v_cvt_pk_bf16_f32 v80, v84, v85
	v_cvt_pk_bf16_f32 v81, v86, v87
	v_cvt_pk_bf16_f32 v82, v88, v89
	v_cvt_pk_bf16_f32 v83, v90, v91
	global_store_dwordx4 v[98:99], v[80:83], off
	s_nop 1
	v_mov_b32_e32 v80, v244
	s_nop 0
	v_or_b32_e32 v82, 48, v164
	v_ashrrev_i32_e32 v83, 31, v82
	v_lshlrev_b64 v[82:83], 10, v[82:83]
	v_lshl_add_u64 v[82:83], v[82:83], 0, v[162:163]
	v_lshlrev_b64 v[82:83], 1, v[82:83]
	v_lshl_add_u64 v[84:85], s[30:31], 0, v[82:83]
	v_lshl_add_u64 v[92:93], s[0:1], 0, v[82:83]
	s_waitcnt vmcnt(13)
; __device__ __forceinline__ unsigned cvt_pk_bf16(float lo, float hi) { const f32x2_cv v = {lo, hi}; const bf16x2_cv b = __builtin_convertvector(v, bf16x2_cv); return __builtin_bit_cast(unsigned, b); }
; __device__ __forceinline__ float sigm(float x) { return __builtin_amdgcn_rcpf(1.0f + __expf(-x)); }
; __device__ __forceinline__ float lo16(unsigned w) { return __uint_as_float(w << 16); }
; __device__ __forceinline__ float hi16(unsigned w) { return __uint_as_float(w & 0xffff0000u); }
; __device__ __forceinline__ float rstd_of(const float* rowss, int row) { return rsqrtf(rowss[row] * (1.0f / 1024.0f) + 1e-6f); }
;     __device__ __forceinline__ void operator()(const f32x4 (&acc)[2][2][4][2], const pg8::Unit& u, int wr, int wc, int fr, int fq) const {
;         const int row0 = u.pm * 256 + wr * 64 + fr, col0 = u.pn * 256 + wc * 32 + 8 * fq;
; #pragma unroll
;         for (int ai = 0; ai < 2; ++ai)
; #pragma unroll
;             for (int m = 0; m < 4; ++m) {
;                 const int row = row0 + ai * 128 + m * 16;
;                 const float s = rstd_of(rowss, row);
; #pragma unroll
;                 for (int bj = 0; bj < 2; ++bj) {
;                     const size_t off = (size_t)row * 1024 + col0 + bj * 128;
;                     const u32x4 tv = *(const u32x4*)(Tm + off);
;                     u32x4 pv = (u32x4){0u, 0u, 0u, 0u};
;                     if (ACC) pv = *(const u32x4*)(M + off);
;                     const f32x4 a0 = acc[ai][bj][m][0] * s, a1 = acc[ai][bj][m][1] * s;
;                     float o[8];
;                     o[0] = sigm(a0[0]) * lo16(tv.x); o[1] = sigm(a0[1]) * hi16(tv.x); o[2] = sigm(a0[2]) * lo16(tv.y); o[3] = sigm(a0[3]) * hi16(tv.y);
;                     o[4] = sigm(a1[0]) * lo16(tv.z); o[5] = sigm(a1[1]) * hi16(tv.z); o[6] = sigm(a1[2]) * lo16(tv.w); o[7] = sigm(a1[3]) * hi16(tv.w);
;                     if (ACC) { o[0] += lo16(pv.x); o[1] += hi16(pv.x); o[2] += lo16(pv.y); o[3] += hi16(pv.y); o[4] += lo16(pv.z); o[5] += hi16(pv.z); o[6] += lo16(pv.w); o[7] += hi16(pv.w); }
;                     u32x4 w; w.x = cvt_pk_bf16(o[0], o[1]); w.y = cvt_pk_bf16(o[2], o[3]); w.z = cvt_pk_bf16(o[4], o[5]); w.w = cvt_pk_bf16(o[6], o[7]);
;                     *(u32x4*)(M + off) = w; } }
	s_nop 1
	v_mov_b32_e32 v84, v192
	v_mov_b32_e32 v85, v193
	v_mov_b32_e32 v86, v194
	v_mov_b32_e32 v87, v195
	v_or_b32_e32 v82, 0x100, v82
	s_nop 1
	v_mov_b32_e32 v88, v196
	v_mov_b32_e32 v89, v197
	v_mov_b32_e32 v90, v198
	v_mov_b32_e32 v91, v199
	v_fmamk_f32 v80, v80, 0x3a800000, v187
	v_cmp_gt_f32_e32 vcc, s67, v80
	v_mul_f32_e32 v81, 0x4b800000, v80
	v_lshlrev_b32_e32 v94, 16, v84
	v_cndmask_b32_e32 v80, v80, v81, vcc
	v_rsq_f32_e32 v80, v80
	v_and_b32_e32 v95, 0xffff0000, v84
	v_lshlrev_b32_e32 v96, 16, v88
	v_and_b32_e32 v97, 0xffff0000, v88
	v_mul_f32_e32 v81, 0x45800000, v80
	v_cndmask_b32_e32 v80, v80, v81, vcc
	v_pk_mul_f32 v[78:79], v[78:79], v[80:81] op_sel_hi:[1,0]
	v_pk_mul_f32 v[72:73], v[72:73], v[80:81] op_sel_hi:[1,0]
	v_mul_f32_e32 v78, 0xbfb8aa3b, v78
	v_mul_f32_e32 v79, 0xbfb8aa3b, v79
	v_pk_mul_f32 v[76:77], v[76:77], v[80:81] op_sel_hi:[1,0]
	v_pk_mul_f32 v[74:75], v[74:75], v[80:81] op_sel_hi:[1,0]
	v_exp_f32_e32 v78, v78
	v_exp_f32_e32 v79, v79
	v_mul_f32_e32 v72, 0xbfb8aa3b, v72
	v_mul_f32_e32 v73, 0xbfb8aa3b, v73
	v_mul_f32_e32 v76, 0xbfb8aa3b, v76
	v_mul_f32_e32 v77, 0xbfb8aa3b, v77
	v_exp_f32_e32 v72, v72
	v_exp_f32_e32 v73, v73
	v_mul_f32_e32 v74, 0xbfb8aa3b, v74
	v_mul_f32_e32 v75, 0xbfb8aa3b, v75
	v_exp_f32_e32 v76, v76
	v_exp_f32_e32 v77, v77
	v_exp_f32_e32 v74, v74
	v_exp_f32_e32 v75, v75
	v_add_f32_e32 v78, 1.0, v78
	v_add_f32_e32 v79, 1.0, v79
	v_rcp_f32_e32 v78, v78
	v_rcp_f32_e32 v79, v79
	v_add_f32_e32 v72, 1.0, v72
	v_add_f32_e32 v73, 1.0, v73
	v_add_f32_e32 v76, 1.0, v76
	v_add_f32_e32 v77, 1.0, v77
	v_rcp_f32_e32 v72, v72
	v_rcp_f32_e32 v73, v73
	v_add_f32_e32 v74, 1.0, v74
	v_add_f32_e32 v75, 1.0, v75
	v_rcp_f32_e32 v76, v76
	v_rcp_f32_e32 v77, v77
	v_rcp_f32_e32 v74, v74
	v_rcp_f32_e32 v75, v75
	v_lshlrev_b32_e32 v84, 16, v85
	v_and_b32_e32 v85, 0xffff0000, v85
	v_lshlrev_b32_e32 v88, 16, v89
	v_and_b32_e32 v89, 0xffff0000, v89
	v_pk_fma_f32 v[78:79], v[78:79], v[84:85], v[88:89]
	v_lshlrev_b32_e32 v84, 16, v86
	v_and_b32_e32 v85, 0xffff0000, v86
	v_lshlrev_b32_e32 v88, 16, v90
	v_and_b32_e32 v89, 0xffff0000, v90
	v_pk_fma_f32 v[84:85], v[72:73], v[84:85], v[88:89]
	v_lshlrev_b32_e32 v72, 16, v87
	v_and_b32_e32 v73, 0xffff0000, v87
	v_lshlrev_b32_e32 v86, 16, v91
	v_and_b32_e32 v87, 0xffff0000, v91
	v_pk_fma_f32 v[76:77], v[76:77], v[94:95], v[96:97]
	v_pk_fma_f32 v[86:87], v[74:75], v[72:73], v[86:87]
	v_cvt_pk_bf16_f32 v72, v76, v77
	v_cvt_pk_bf16_f32 v73, v78, v79
	v_cvt_pk_bf16_f32 v74, v84, v85
	v_cvt_pk_bf16_f32 v75, v86, v87
	global_store_dwordx4 v[92:93], v[72:75], off
	v_pk_mul_f32 v[70:71], v[70:71], v[80:81] op_sel_hi:[1,0]
	v_pk_mul_f32 v[64:65], v[64:65], v[80:81] op_sel_hi:[1,0]
	v_lshl_add_u64 v[72:73], s[30:31], 0, v[82:83]
	v_lshl_add_u64 v[82:83], s[0:1], 0, v[82:83]
	s_nop 1
	v_mov_b32_e32 v76, v200
	v_mov_b32_e32 v77, v201
	v_mov_b32_e32 v78, v202
	v_mov_b32_e32 v79, v203
	v_mul_f32_e32 v70, 0xbfb8aa3b, v70
	s_nop 1
	v_mov_b32_e32 v72, v204
	v_mov_b32_e32 v73, v205
	v_mov_b32_e32 v74, v206
	v_mov_b32_e32 v75, v207
	v_add_u32_e32 v250, 0x50000, v249
	global_load_dwordx4 v[192:195], v250, s[30:31]
	global_load_dwordx4 v[196:199], v250, s[0:1]
	global_load_dwordx4 v[200:203], v250, s[30:31] offset:256
	global_load_dwordx4 v[204:207], v250, s[0:1] offset:256
	v_mul_f32_e32 v71, 0xbfb8aa3b, v71
	v_pk_mul_f32 v[68:69], v[68:69], v[80:81] op_sel_hi:[1,0]
	v_pk_mul_f32 v[66:67], v[66:67], v[80:81] op_sel_hi:[1,0]
	v_exp_f32_e32 v70, v70
	v_exp_f32_e32 v71, v71
	v_mul_f32_e32 v64, 0xbfb8aa3b, v64
	v_mul_f32_e32 v65, 0xbfb8aa3b, v65
	v_mul_f32_e32 v68, 0xbfb8aa3b, v68
	v_mul_f32_e32 v69, 0xbfb8aa3b, v69
	v_exp_f32_e32 v64, v64
	v_exp_f32_e32 v65, v65
	v_mul_f32_e32 v66, 0xbfb8aa3b, v66
	v_mul_f32_e32 v67, 0xbfb8aa3b, v67
	v_exp_f32_e32 v68, v68
	v_exp_f32_e32 v69, v69
	v_exp_f32_e32 v66, v66
	v_exp_f32_e32 v67, v67
	v_add_f32_e32 v70, 1.0, v70
	v_add_f32_e32 v71, 1.0, v71
	v_rcp_f32_e32 v70, v70
	v_rcp_f32_e32 v71, v71
	v_add_f32_e32 v64, 1.0, v64
	v_add_f32_e32 v65, 1.0, v65
	v_add_f32_e32 v68, 1.0, v68
	v_add_f32_e32 v69, 1.0, v69
	v_rcp_f32_e32 v64, v64
	v_rcp_f32_e32 v65, v65
	v_add_f32_e32 v66, 1.0, v66
	v_add_f32_e32 v67, 1.0, v67
	v_rcp_f32_e32 v68, v68
	v_rcp_f32_e32 v69, v69
	v_rcp_f32_e32 v66, v66
	v_rcp_f32_e32 v67, v67
	v_lshlrev_b32_e32 v80, 16, v76
	v_and_b32_e32 v81, 0xffff0000, v76
	v_lshlrev_b32_e32 v84, 16, v72
	v_and_b32_e32 v85, 0xffff0000, v72
	v_lshlrev_b32_e32 v76, 16, v77
	v_and_b32_e32 v77, 0xffff0000, v77
	v_lshlrev_b32_e32 v72, 16, v73
	v_and_b32_e32 v73, 0xffff0000, v73
	v_pk_fma_f32 v[70:71], v[70:71], v[76:77], v[72:73]
	v_lshlrev_b32_e32 v72, 16, v78
	v_and_b32_e32 v73, 0xffff0000, v78
	v_lshlrev_b32_e32 v76, 16, v74
	v_and_b32_e32 v77, 0xffff0000, v74
	v_pk_fma_f32 v[72:73], v[64:65], v[72:73], v[76:77]
	v_lshlrev_b32_e32 v64, 16, v79
	v_and_b32_e32 v65, 0xffff0000, v79
	v_lshlrev_b32_e32 v74, 16, v75
	v_and_b32_e32 v75, 0xffff0000, v75
	v_pk_fma_f32 v[68:69], v[68:69], v[80:81], v[84:85]
	v_pk_fma_f32 v[74:75], v[66:67], v[64:65], v[74:75]
	v_cvt_pk_bf16_f32 v64, v68, v69
	v_cvt_pk_bf16_f32 v65, v70, v71
	v_cvt_pk_bf16_f32 v66, v72, v73
	v_cvt_pk_bf16_f32 v67, v74, v75
	global_store_dwordx4 v[82:83], v[64:67], off
	s_nop 1
	v_mov_b32_e32 v64, v245
	v_lshl_add_u64 v[70:71], v[158:159], 0, s[2:3]
	v_lshl_add_u64 v[66:67], s[30:31], 0, v[70:71]
	v_lshl_add_u64 v[74:75], s[0:1], 0, v[70:71]
	s_waitcnt vmcnt(13)
; __device__ __forceinline__ unsigned cvt_pk_bf16(float lo, float hi) { const f32x2_cv v = {lo, hi}; const bf16x2_cv b = __builtin_convertvector(v, bf16x2_cv); return __builtin_bit_cast(unsigned, b); }
; __device__ __forceinline__ float sigm(float x) { return __builtin_amdgcn_rcpf(1.0f + __expf(-x)); }
; __device__ __forceinline__ float lo16(unsigned w) { return __uint_as_float(w << 16); }
; __device__ __forceinline__ float hi16(unsigned w) { return __uint_as_float(w & 0xffff0000u); }
; __device__ __forceinline__ float rstd_of(const float* rowss, int row) { return rsqrtf(rowss[row] * (1.0f / 1024.0f) + 1e-6f); }
;     __device__ __forceinline__ void operator()(const f32x4 (&acc)[2][2][4][2], const pg8::Unit& u, int wr, int wc, int fr, int fq) const {
;         const int row0 = u.pm * 256 + wr * 64 + fr, col0 = u.pn * 256 + wc * 32 + 8 * fq;
; #pragma unroll
;         for (int ai = 0; ai < 2; ++ai)
; #pragma unroll
;             for (int m = 0; m < 4; ++m) {
;                 const int row = row0 + ai * 128 + m * 16;
;                 const float s = rstd_of(rowss, row);
; #pragma unroll
;                 for (int bj = 0; bj < 2; ++bj) {
;                     const size_t off = (size_t)row * 1024 + col0 + bj * 128;
;                     const u32x4 tv = *(const u32x4*)(Tm + off);
;                     u32x4 pv = (u32x4){0u, 0u, 0u, 0u};
;                     if (ACC) pv = *(const u32x4*)(M + off);
;                     const f32x4 a0 = acc[ai][bj][m][0] * s, a1 = acc[ai][bj][m][1] * s;
;                     float o[8];
;                     o[0] = sigm(a0[0]) * lo16(tv.x); o[1] = sigm(a0[1]) * hi16(tv.x); o[2] = sigm(a0[2]) * lo16(tv.y); o[3] = sigm(a0[3]) * hi16(tv.y);
;                     o[4] = sigm(a1[0]) * lo16(tv.z); o[5] = sigm(a1[1]) * hi16(tv.z); o[6] = sigm(a1[2]) * lo16(tv.w); o[7] = sigm(a1[3]) * hi16(tv.w);
;                     if (ACC) { o[0] += lo16(pv.x); o[1] += hi16(pv.x); o[2] += lo16(pv.y); o[3] += hi16(pv.y); o[4] += lo16(pv.z); o[5] += hi16(pv.z); o[6] += lo16(pv.w); o[7] += hi16(pv.w); }
;                     u32x4 w; w.x = cvt_pk_bf16(o[0], o[1]); w.y = cvt_pk_bf16(o[2], o[3]); w.z = cvt_pk_bf16(o[4], o[5]); w.w = cvt_pk_bf16(o[6], o[7]);
;                     *(u32x4*)(M + off) = w; } }
	s_nop 1
	v_mov_b32_e32 v66, v208
	v_mov_b32_e32 v67, v209
	v_mov_b32_e32 v68, v210
	v_mov_b32_e32 v69, v211
	s_mov_b64 s[2:3], 0x40100
	s_nop 1
	v_mov_b32_e32 v70, v212
	v_mov_b32_e32 v71, v213
	v_mov_b32_e32 v72, v214
	v_mov_b32_e32 v73, v215
	v_fmamk_f32 v64, v64, 0x3a800000, v187
	v_cmp_gt_f32_e32 vcc, s67, v64
	v_mul_f32_e32 v65, 0x4b800000, v64
	v_lshlrev_b32_e32 v76, 16, v66
	v_cndmask_b32_e32 v64, v64, v65, vcc
	v_rsq_f32_e32 v64, v64
	v_and_b32_e32 v77, 0xffff0000, v66
	v_lshlrev_b32_e32 v78, 16, v70
	v_and_b32_e32 v79, 0xffff0000, v70
	v_mul_f32_e32 v65, 0x45800000, v64
	v_cndmask_b32_e32 v64, v64, v65, vcc
	v_pk_mul_f32 v[62:63], v[62:63], v[64:65] op_sel_hi:[1,0]
	v_pk_mul_f32 v[56:57], v[56:57], v[64:65] op_sel_hi:[1,0]
	v_mul_f32_e32 v62, 0xbfb8aa3b, v62
	v_mul_f32_e32 v63, 0xbfb8aa3b, v63
	v_pk_mul_f32 v[60:61], v[60:61], v[64:65] op_sel_hi:[1,0]
	v_pk_mul_f32 v[58:59], v[58:59], v[64:65] op_sel_hi:[1,0]
	v_exp_f32_e32 v62, v62
	v_exp_f32_e32 v63, v63
	v_mul_f32_e32 v56, 0xbfb8aa3b, v56
	v_mul_f32_e32 v57, 0xbfb8aa3b, v57
	v_mul_f32_e32 v60, 0xbfb8aa3b, v60
	v_mul_f32_e32 v61, 0xbfb8aa3b, v61
	v_exp_f32_e32 v56, v56
	v_exp_f32_e32 v57, v57
	v_mul_f32_e32 v58, 0xbfb8aa3b, v58
	v_mul_f32_e32 v59, 0xbfb8aa3b, v59
	v_exp_f32_e32 v60, v60
	v_exp_f32_e32 v61, v61
	v_exp_f32_e32 v58, v58
	v_exp_f32_e32 v59, v59
	v_add_f32_e32 v62, 1.0, v62
	v_add_f32_e32 v63, 1.0, v63
	v_rcp_f32_e32 v62, v62
	v_rcp_f32_e32 v63, v63
	v_add_f32_e32 v56, 1.0, v56
	v_add_f32_e32 v57, 1.0, v57
	v_add_f32_e32 v60, 1.0, v60
	v_add_f32_e32 v61, 1.0, v61
	v_rcp_f32_e32 v56, v56
	v_rcp_f32_e32 v57, v57
	v_add_f32_e32 v58, 1.0, v58
	v_add_f32_e32 v59, 1.0, v59
	v_rcp_f32_e32 v60, v60
	v_rcp_f32_e32 v61, v61
	v_rcp_f32_e32 v58, v58
	v_rcp_f32_e32 v59, v59
	v_lshlrev_b32_e32 v66, 16, v67
	v_and_b32_e32 v67, 0xffff0000, v67
	v_lshlrev_b32_e32 v70, 16, v71
	v_and_b32_e32 v71, 0xffff0000, v71
	v_pk_fma_f32 v[62:63], v[62:63], v[66:67], v[70:71]
	v_lshlrev_b32_e32 v66, 16, v68
	v_and_b32_e32 v67, 0xffff0000, v68
	v_lshlrev_b32_e32 v70, 16, v72
	v_and_b32_e32 v71, 0xffff0000, v72
	v_pk_fma_f32 v[66:67], v[56:57], v[66:67], v[70:71]
	v_lshlrev_b32_e32 v56, 16, v69
	v_and_b32_e32 v57, 0xffff0000, v69
	v_lshlrev_b32_e32 v68, 16, v73
	v_and_b32_e32 v69, 0xffff0000, v73
	v_pk_fma_f32 v[60:61], v[60:61], v[76:77], v[78:79]
	v_pk_fma_f32 v[68:69], v[58:59], v[56:57], v[68:69]
	v_cvt_pk_bf16_f32 v56, v60, v61
	v_cvt_pk_bf16_f32 v57, v62, v63
	v_cvt_pk_bf16_f32 v58, v66, v67
	v_cvt_pk_bf16_f32 v59, v68, v69
	global_store_dwordx4 v[74:75], v[56:59], off
	v_pk_mul_f32 v[54:55], v[54:55], v[64:65] op_sel_hi:[1,0]
	v_pk_mul_f32 v[48:49], v[48:49], v[64:65] op_sel_hi:[1,0]
	v_lshl_add_u64 v[56:57], v[158:159], 0, s[2:3]
	v_lshl_add_u64 v[58:59], s[30:31], 0, v[56:57]
	v_lshl_add_u64 v[66:67], s[0:1], 0, v[56:57]
	s_nop 1
	v_mov_b32_e32 v60, v216
	v_mov_b32_e32 v61, v217
	v_mov_b32_e32 v62, v218
	v_mov_b32_e32 v63, v219
	v_mul_f32_e32 v54, 0xbfb8aa3b, v54
	s_nop 1
	v_mov_b32_e32 v56, v220
	v_mov_b32_e32 v57, v221
	v_mov_b32_e32 v58, v222
	v_mov_b32_e32 v59, v223
	v_add_u32_e32 v250, 0x58000, v249
	global_load_dwordx4 v[208:211], v250, s[30:31]
	global_load_dwordx4 v[212:215], v250, s[0:1]
	global_load_dwordx4 v[216:219], v250, s[30:31] offset:256
	global_load_dwordx4 v[220:223], v250, s[0:1] offset:256
	v_mul_f32_e32 v55, 0xbfb8aa3b, v55
	v_pk_mul_f32 v[52:53], v[52:53], v[64:65] op_sel_hi:[1,0]
	v_pk_mul_f32 v[50:51], v[50:51], v[64:65] op_sel_hi:[1,0]
	v_exp_f32_e32 v54, v54
	v_exp_f32_e32 v55, v55
	v_mul_f32_e32 v48, 0xbfb8aa3b, v48
	v_mul_f32_e32 v49, 0xbfb8aa3b, v49
	v_mul_f32_e32 v52, 0xbfb8aa3b, v52
	v_mul_f32_e32 v53, 0xbfb8aa3b, v53
	v_exp_f32_e32 v48, v48
	v_exp_f32_e32 v49, v49
	v_mul_f32_e32 v50, 0xbfb8aa3b, v50
	v_mul_f32_e32 v51, 0xbfb8aa3b, v51
	v_exp_f32_e32 v52, v52
	v_exp_f32_e32 v53, v53
	v_exp_f32_e32 v50, v50
	v_exp_f32_e32 v51, v51
	v_add_f32_e32 v54, 1.0, v54
	v_add_f32_e32 v55, 1.0, v55
	v_rcp_f32_e32 v54, v54
	v_rcp_f32_e32 v55, v55
	v_add_f32_e32 v48, 1.0, v48
	v_add_f32_e32 v49, 1.0, v49
	v_add_f32_e32 v52, 1.0, v52
	v_add_f32_e32 v53, 1.0, v53
	v_rcp_f32_e32 v48, v48
	v_rcp_f32_e32 v49, v49
	v_add_f32_e32 v50, 1.0, v50
	v_add_f32_e32 v51, 1.0, v51
	v_rcp_f32_e32 v52, v52
	v_rcp_f32_e32 v53, v53
	v_rcp_f32_e32 v50, v50
	v_rcp_f32_e32 v51, v51
	s_mov_b64 s[2:3], 0x48000
	v_lshlrev_b32_e32 v64, 16, v60
	v_and_b32_e32 v65, 0xffff0000, v60
	v_lshlrev_b32_e32 v68, 16, v56
	v_and_b32_e32 v69, 0xffff0000, v56
	v_lshlrev_b32_e32 v60, 16, v61
	v_and_b32_e32 v61, 0xffff0000, v61
	v_lshlrev_b32_e32 v56, 16, v57
	v_and_b32_e32 v57, 0xffff0000, v57
	v_pk_fma_f32 v[54:55], v[54:55], v[60:61], v[56:57]
	v_lshlrev_b32_e32 v56, 16, v62
	v_and_b32_e32 v57, 0xffff0000, v62
	v_lshlrev_b32_e32 v60, 16, v58
	v_and_b32_e32 v61, 0xffff0000, v58
	v_pk_fma_f32 v[56:57], v[48:49], v[56:57], v[60:61]
	v_lshlrev_b32_e32 v48, 16, v63
	v_and_b32_e32 v49, 0xffff0000, v63
	v_lshlrev_b32_e32 v58, 16, v59
	v_and_b32_e32 v59, 0xffff0000, v59
	v_pk_fma_f32 v[52:53], v[52:53], v[64:65], v[68:69]
	v_pk_fma_f32 v[58:59], v[50:51], v[48:49], v[58:59]
	v_cvt_pk_bf16_f32 v48, v52, v53
	v_cvt_pk_bf16_f32 v49, v54, v55
	v_cvt_pk_bf16_f32 v50, v56, v57
	v_cvt_pk_bf16_f32 v51, v58, v59
	global_store_dwordx4 v[66:67], v[48:51], off
	s_nop 1
	v_mov_b32_e32 v48, v246
	v_lshl_add_u64 v[54:55], v[158:159], 0, s[2:3]
	v_lshl_add_u64 v[50:51], s[30:31], 0, v[54:55]
	v_lshl_add_u64 v[58:59], s[0:1], 0, v[54:55]
	s_waitcnt vmcnt(13)
; __device__ __forceinline__ unsigned cvt_pk_bf16(float lo, float hi) { const f32x2_cv v = {lo, hi}; const bf16x2_cv b = __builtin_convertvector(v, bf16x2_cv); return __builtin_bit_cast(unsigned, b); }
; __device__ __forceinline__ float sigm(float x) { return __builtin_amdgcn_rcpf(1.0f + __expf(-x)); }
; __device__ __forceinline__ float lo16(unsigned w) { return __uint_as_float(w << 16); }
; __device__ __forceinline__ float hi16(unsigned w) { return __uint_as_float(w & 0xffff0000u); }
; __device__ __forceinline__ float rstd_of(const float* rowss, int row) { return rsqrtf(rowss[row] * (1.0f / 1024.0f) + 1e-6f); }
;     __device__ __forceinline__ void operator()(const f32x4 (&acc)[2][2][4][2], const pg8::Unit& u, int wr, int wc, int fr, int fq) const {
;         const int row0 = u.pm * 256 + wr * 64 + fr, col0 = u.pn * 256 + wc * 32 + 8 * fq;
; #pragma unroll
;         for (int ai = 0; ai < 2; ++ai)
; #pragma unroll
;             for (int m = 0; m < 4; ++m) {
;                 const int row = row0 + ai * 128 + m * 16;
;                 const float s = rstd_of(rowss, row);
; #pragma unroll
;                 for (int bj = 0; bj < 2; ++bj) {
;                     const size_t off = (size_t)row * 1024 + col0 + bj * 128;
;                     const u32x4 tv = *(const u32x4*)(Tm + off);
;                     u32x4 pv = (u32x4){0u, 0u, 0u, 0u};
;                     if (ACC) pv = *(const u32x4*)(M + off);
;                     const f32x4 a0 = acc[ai][bj][m][0] * s, a1 = acc[ai][bj][m][1] * s;
;                     float o[8];
;                     o[0] = sigm(a0[0]) * lo16(tv.x); o[1] = sigm(a0[1]) * hi16(tv.x); o[2] = sigm(a0[2]) * lo16(tv.y); o[3] = sigm(a0[3]) * hi16(tv.y);
;                     o[4] = sigm(a1[0]) * lo16(tv.z); o[5] = sigm(a1[1]) * hi16(tv.z); o[6] = sigm(a1[2]) * lo16(tv.w); o[7] = sigm(a1[3]) * hi16(tv.w);
;                     if (ACC) { o[0] += lo16(pv.x); o[1] += hi16(pv.x); o[2] += lo16(pv.y); o[3] += hi16(pv.y); o[4] += lo16(pv.z); o[5] += hi16(pv.z); o[6] += lo16(pv.w); o[7] += hi16(pv.w); }
;                     u32x4 w; w.x = cvt_pk_bf16(o[0], o[1]); w.y = cvt_pk_bf16(o[2], o[3]); w.z = cvt_pk_bf16(o[4], o[5]); w.w = cvt_pk_bf16(o[6], o[7]);
;                     *(u32x4*)(M + off) = w; } }
	s_nop 1
	v_mov_b32_e32 v50, v224
	v_mov_b32_e32 v51, v225
	v_mov_b32_e32 v52, v226
	v_mov_b32_e32 v53, v227
	s_mov_b64 s[2:3], 0x48100
	s_nop 1
	v_mov_b32_e32 v54, v228
	v_mov_b32_e32 v55, v229
	v_mov_b32_e32 v56, v230
	v_mov_b32_e32 v57, v231
	v_fmamk_f32 v48, v48, 0x3a800000, v187
	v_cmp_gt_f32_e32 vcc, s67, v48
	v_mul_f32_e32 v49, 0x4b800000, v48
	v_lshlrev_b32_e32 v60, 16, v50
	v_cndmask_b32_e32 v48, v48, v49, vcc
	v_rsq_f32_e32 v48, v48
	v_and_b32_e32 v61, 0xffff0000, v50
	v_lshlrev_b32_e32 v62, 16, v54
	v_and_b32_e32 v63, 0xffff0000, v54
	v_mul_f32_e32 v49, 0x45800000, v48
	v_cndmask_b32_e32 v48, v48, v49, vcc
	v_pk_mul_f32 v[46:47], v[46:47], v[48:49] op_sel_hi:[1,0]
	v_pk_mul_f32 v[40:41], v[40:41], v[48:49] op_sel_hi:[1,0]
	v_mul_f32_e32 v46, 0xbfb8aa3b, v46
	v_mul_f32_e32 v47, 0xbfb8aa3b, v47
	v_pk_mul_f32 v[44:45], v[44:45], v[48:49] op_sel_hi:[1,0]
	v_pk_mul_f32 v[42:43], v[42:43], v[48:49] op_sel_hi:[1,0]
	v_exp_f32_e32 v46, v46
	v_exp_f32_e32 v47, v47
	v_mul_f32_e32 v40, 0xbfb8aa3b, v40
	v_mul_f32_e32 v41, 0xbfb8aa3b, v41
	v_mul_f32_e32 v44, 0xbfb8aa3b, v44
	v_mul_f32_e32 v45, 0xbfb8aa3b, v45
	v_exp_f32_e32 v40, v40
	v_exp_f32_e32 v41, v41
	v_mul_f32_e32 v42, 0xbfb8aa3b, v42
	v_mul_f32_e32 v43, 0xbfb8aa3b, v43
	v_exp_f32_e32 v44, v44
	v_exp_f32_e32 v45, v45
	v_exp_f32_e32 v42, v42
	v_exp_f32_e32 v43, v43
	v_add_f32_e32 v46, 1.0, v46
	v_add_f32_e32 v47, 1.0, v47
	v_rcp_f32_e32 v46, v46
	v_rcp_f32_e32 v47, v47
	v_add_f32_e32 v40, 1.0, v40
	v_add_f32_e32 v41, 1.0, v41
	v_add_f32_e32 v44, 1.0, v44
	v_add_f32_e32 v45, 1.0, v45
	v_rcp_f32_e32 v40, v40
	v_rcp_f32_e32 v41, v41
	v_add_f32_e32 v42, 1.0, v42
	v_add_f32_e32 v43, 1.0, v43
	v_rcp_f32_e32 v44, v44
	v_rcp_f32_e32 v45, v45
	v_rcp_f32_e32 v42, v42
	v_rcp_f32_e32 v43, v43
	v_lshlrev_b32_e32 v50, 16, v51
	v_and_b32_e32 v51, 0xffff0000, v51
	v_lshlrev_b32_e32 v54, 16, v55
	v_and_b32_e32 v55, 0xffff0000, v55
	v_pk_fma_f32 v[46:47], v[46:47], v[50:51], v[54:55]
	v_lshlrev_b32_e32 v50, 16, v52
	v_and_b32_e32 v51, 0xffff0000, v52
	v_lshlrev_b32_e32 v54, 16, v56
	v_and_b32_e32 v55, 0xffff0000, v56
	v_pk_fma_f32 v[50:51], v[40:41], v[50:51], v[54:55]
	v_lshlrev_b32_e32 v40, 16, v53
	v_and_b32_e32 v41, 0xffff0000, v53
	v_lshlrev_b32_e32 v52, 16, v57
	v_and_b32_e32 v53, 0xffff0000, v57
	v_pk_fma_f32 v[44:45], v[44:45], v[60:61], v[62:63]
	v_pk_fma_f32 v[52:53], v[42:43], v[40:41], v[52:53]
	v_cvt_pk_bf16_f32 v40, v44, v45
	v_cvt_pk_bf16_f32 v41, v46, v47
	v_cvt_pk_bf16_f32 v42, v50, v51
	v_cvt_pk_bf16_f32 v43, v52, v53
	global_store_dwordx4 v[58:59], v[40:43], off
	v_pk_mul_f32 v[38:39], v[38:39], v[48:49] op_sel_hi:[1,0]
	v_pk_mul_f32 v[32:33], v[32:33], v[48:49] op_sel_hi:[1,0]
	v_lshl_add_u64 v[40:41], v[158:159], 0, s[2:3]
	v_lshl_add_u64 v[42:43], s[30:31], 0, v[40:41]
	v_lshl_add_u64 v[50:51], s[0:1], 0, v[40:41]
	s_nop 1
	v_mov_b32_e32 v44, v232
	v_mov_b32_e32 v45, v233
	v_mov_b32_e32 v46, v234
	v_mov_b32_e32 v47, v235
	v_mul_f32_e32 v38, 0xbfb8aa3b, v38
	s_nop 1
	v_mov_b32_e32 v40, v236
	v_mov_b32_e32 v41, v237
	v_mov_b32_e32 v42, v238
	v_mov_b32_e32 v43, v239
	v_mul_f32_e32 v39, 0xbfb8aa3b, v39
	v_pk_mul_f32 v[36:37], v[36:37], v[48:49] op_sel_hi:[1,0]
	v_pk_mul_f32 v[34:35], v[34:35], v[48:49] op_sel_hi:[1,0]
	v_exp_f32_e32 v38, v38
	v_exp_f32_e32 v39, v39
	v_mul_f32_e32 v32, 0xbfb8aa3b, v32
	v_mul_f32_e32 v33, 0xbfb8aa3b, v33
	v_mul_f32_e32 v36, 0xbfb8aa3b, v36
	v_mul_f32_e32 v37, 0xbfb8aa3b, v37
	v_exp_f32_e32 v32, v32
	v_exp_f32_e32 v33, v33
	v_mul_f32_e32 v34, 0xbfb8aa3b, v34
	v_mul_f32_e32 v35, 0xbfb8aa3b, v35
	v_exp_f32_e32 v36, v36
	v_exp_f32_e32 v37, v37
	v_exp_f32_e32 v34, v34
	v_exp_f32_e32 v35, v35
	v_add_f32_e32 v38, 1.0, v38
	v_add_f32_e32 v39, 1.0, v39
	v_rcp_f32_e32 v38, v38
	v_rcp_f32_e32 v39, v39
	v_add_f32_e32 v32, 1.0, v32
	v_add_f32_e32 v33, 1.0, v33
	v_add_f32_e32 v36, 1.0, v36
	v_add_f32_e32 v37, 1.0, v37
	v_rcp_f32_e32 v32, v32
	v_rcp_f32_e32 v33, v33
	v_add_f32_e32 v34, 1.0, v34
	v_add_f32_e32 v35, 1.0, v35
	v_rcp_f32_e32 v36, v36
	v_rcp_f32_e32 v37, v37
	v_rcp_f32_e32 v34, v34
	v_rcp_f32_e32 v35, v35
	s_mov_b64 s[2:3], 0x50000
	v_lshlrev_b32_e32 v48, 16, v44
	v_and_b32_e32 v49, 0xffff0000, v44
	v_lshlrev_b32_e32 v52, 16, v40
	v_and_b32_e32 v53, 0xffff0000, v40
	v_lshlrev_b32_e32 v44, 16, v45
	v_and_b32_e32 v45, 0xffff0000, v45
	v_lshlrev_b32_e32 v40, 16, v41
	v_and_b32_e32 v41, 0xffff0000, v41
	v_pk_fma_f32 v[38:39], v[38:39], v[44:45], v[40:41]
	v_lshlrev_b32_e32 v40, 16, v46
	v_and_b32_e32 v41, 0xffff0000, v46
	v_lshlrev_b32_e32 v44, 16, v42
	v_and_b32_e32 v45, 0xffff0000, v42
	v_pk_fma_f32 v[40:41], v[32:33], v[40:41], v[44:45]
	v_lshlrev_b32_e32 v32, 16, v47
	v_and_b32_e32 v33, 0xffff0000, v47
	v_lshlrev_b32_e32 v42, 16, v43
	v_and_b32_e32 v43, 0xffff0000, v43
	v_pk_fma_f32 v[36:37], v[36:37], v[48:49], v[52:53]
	v_pk_fma_f32 v[42:43], v[34:35], v[32:33], v[42:43]
	v_cvt_pk_bf16_f32 v32, v36, v37
	v_cvt_pk_bf16_f32 v33, v38, v39
	v_cvt_pk_bf16_f32 v34, v40, v41
	v_cvt_pk_bf16_f32 v35, v42, v43
	global_store_dwordx4 v[50:51], v[32:35], off
	s_nop 1
	v_mov_b32_e32 v32, v247
	v_lshl_add_u64 v[38:39], v[158:159], 0, s[2:3]
	v_lshl_add_u64 v[34:35], s[30:31], 0, v[38:39]
	v_lshl_add_u64 v[42:43], s[0:1], 0, v[38:39]
	s_waitcnt vmcnt(9)
; __device__ __forceinline__ unsigned cvt_pk_bf16(float lo, float hi) { const f32x2_cv v = {lo, hi}; const bf16x2_cv b = __builtin_convertvector(v, bf16x2_cv); return __builtin_bit_cast(unsigned, b); }
; __device__ __forceinline__ float sigm(float x) { return __builtin_amdgcn_rcpf(1.0f + __expf(-x)); }
; __device__ __forceinline__ float lo16(unsigned w) { return __uint_as_float(w << 16); }
; __device__ __forceinline__ float hi16(unsigned w) { return __uint_as_float(w & 0xffff0000u); }
; __device__ __forceinline__ float rstd_of(const float* rowss, int row) { return rsqrtf(rowss[row] * (1.0f / 1024.0f) + 1e-6f); }
;     __device__ __forceinline__ void operator()(const f32x4 (&acc)[2][2][4][2], const pg8::Unit& u, int wr, int wc, int fr, int fq) const {
;         const int row0 = u.pm * 256 + wr * 64 + fr, col0 = u.pn * 256 + wc * 32 + 8 * fq;
; #pragma unroll
;         for (int ai = 0; ai < 2; ++ai)
; #pragma unroll
;             for (int m = 0; m < 4; ++m) {
;                 const int row = row0 + ai * 128 + m * 16;
;                 const float s = rstd_of(rowss, row);
; #pragma unroll
;                 for (int bj = 0; bj < 2; ++bj) {
;                     const size_t off = (size_t)row * 1024 + col0 + bj * 128;
;                     const u32x4 tv = *(const u32x4*)(Tm + off);
;                     u32x4 pv = (u32x4){0u, 0u, 0u, 0u};
;                     if (ACC) pv = *(const u32x4*)(M + off);
;                     const f32x4 a0 = acc[ai][bj][m][0] * s, a1 = acc[ai][bj][m][1] * s;
;                     float o[8];
;                     o[0] = sigm(a0[0]) * lo16(tv.x); o[1] = sigm(a0[1]) * hi16(tv.x); o[2] = sigm(a0[2]) * lo16(tv.y); o[3] = sigm(a0[3]) * hi16(tv.y);
;                     o[4] = sigm(a1[0]) * lo16(tv.z); o[5] = sigm(a1[1]) * hi16(tv.z); o[6] = sigm(a1[2]) * lo16(tv.w); o[7] = sigm(a1[3]) * hi16(tv.w);
;                     if (ACC) { o[0] += lo16(pv.x); o[1] += hi16(pv.x); o[2] += lo16(pv.y); o[3] += hi16(pv.y); o[4] += lo16(pv.z); o[5] += hi16(pv.z); o[6] += lo16(pv.w); o[7] += hi16(pv.w); }
;                     u32x4 w; w.x = cvt_pk_bf16(o[0], o[1]); w.y = cvt_pk_bf16(o[2], o[3]); w.z = cvt_pk_bf16(o[4], o[5]); w.w = cvt_pk_bf16(o[6], o[7]);
;                     *(u32x4*)(M + off) = w; } }
	s_nop 1
	v_mov_b32_e32 v34, v192
	v_mov_b32_e32 v35, v193
	v_mov_b32_e32 v36, v194
	v_mov_b32_e32 v37, v195
	s_mov_b64 s[2:3], 0x50100
	s_nop 1
	v_mov_b32_e32 v38, v196
	v_mov_b32_e32 v39, v197
	v_mov_b32_e32 v40, v198
	v_mov_b32_e32 v41, v199
	v_fmamk_f32 v32, v32, 0x3a800000, v187
	v_cmp_gt_f32_e32 vcc, s67, v32
	v_mul_f32_e32 v33, 0x4b800000, v32
	v_lshlrev_b32_e32 v44, 16, v34
	v_cndmask_b32_e32 v32, v32, v33, vcc
	v_rsq_f32_e32 v32, v32
	v_and_b32_e32 v45, 0xffff0000, v34
	v_lshlrev_b32_e32 v46, 16, v38
	v_and_b32_e32 v47, 0xffff0000, v38
	v_mul_f32_e32 v33, 0x45800000, v32
	v_cndmask_b32_e32 v32, v32, v33, vcc
	v_pk_mul_f32 v[30:31], v[30:31], v[32:33] op_sel_hi:[1,0]
	v_pk_mul_f32 v[24:25], v[24:25], v[32:33] op_sel_hi:[1,0]
	v_mul_f32_e32 v30, 0xbfb8aa3b, v30
	v_mul_f32_e32 v31, 0xbfb8aa3b, v31
	v_pk_mul_f32 v[28:29], v[28:29], v[32:33] op_sel_hi:[1,0]
	v_pk_mul_f32 v[26:27], v[26:27], v[32:33] op_sel_hi:[1,0]
	v_exp_f32_e32 v30, v30
	v_exp_f32_e32 v31, v31
	v_mul_f32_e32 v24, 0xbfb8aa3b, v24
	v_mul_f32_e32 v25, 0xbfb8aa3b, v25
	v_mul_f32_e32 v28, 0xbfb8aa3b, v28
	v_mul_f32_e32 v29, 0xbfb8aa3b, v29
	v_exp_f32_e32 v24, v24
	v_exp_f32_e32 v25, v25
	v_mul_f32_e32 v26, 0xbfb8aa3b, v26
	v_mul_f32_e32 v27, 0xbfb8aa3b, v27
	v_exp_f32_e32 v28, v28
	v_exp_f32_e32 v29, v29
	v_exp_f32_e32 v26, v26
	v_exp_f32_e32 v27, v27
	v_add_f32_e32 v30, 1.0, v30
	v_add_f32_e32 v31, 1.0, v31
	v_rcp_f32_e32 v30, v30
	v_rcp_f32_e32 v31, v31
	v_add_f32_e32 v24, 1.0, v24
	v_add_f32_e32 v25, 1.0, v25
	v_add_f32_e32 v28, 1.0, v28
	v_add_f32_e32 v29, 1.0, v29
	v_rcp_f32_e32 v24, v24
	v_rcp_f32_e32 v25, v25
	v_add_f32_e32 v26, 1.0, v26
	v_add_f32_e32 v27, 1.0, v27
	v_rcp_f32_e32 v28, v28
	v_rcp_f32_e32 v29, v29
	v_rcp_f32_e32 v26, v26
	v_rcp_f32_e32 v27, v27
	v_lshlrev_b32_e32 v34, 16, v35
	v_and_b32_e32 v35, 0xffff0000, v35
	v_lshlrev_b32_e32 v38, 16, v39
	v_and_b32_e32 v39, 0xffff0000, v39
	v_pk_fma_f32 v[30:31], v[30:31], v[34:35], v[38:39]
	v_lshlrev_b32_e32 v34, 16, v36
	v_and_b32_e32 v35, 0xffff0000, v36
	v_lshlrev_b32_e32 v38, 16, v40
	v_and_b32_e32 v39, 0xffff0000, v40
	v_pk_fma_f32 v[34:35], v[24:25], v[34:35], v[38:39]
	v_lshlrev_b32_e32 v24, 16, v37
	v_and_b32_e32 v25, 0xffff0000, v37
	v_lshlrev_b32_e32 v36, 16, v41
	v_and_b32_e32 v37, 0xffff0000, v41
	v_pk_fma_f32 v[28:29], v[28:29], v[44:45], v[46:47]
	v_pk_fma_f32 v[36:37], v[26:27], v[24:25], v[36:37]
	v_cvt_pk_bf16_f32 v24, v28, v29
	v_cvt_pk_bf16_f32 v25, v30, v31
	v_cvt_pk_bf16_f32 v26, v34, v35
	v_cvt_pk_bf16_f32 v27, v36, v37
	global_store_dwordx4 v[42:43], v[24:27], off
	v_pk_mul_f32 v[22:23], v[22:23], v[32:33] op_sel_hi:[1,0]
	v_pk_mul_f32 v[16:17], v[16:17], v[32:33] op_sel_hi:[1,0]
	v_lshl_add_u64 v[24:25], v[158:159], 0, s[2:3]
	v_lshl_add_u64 v[26:27], s[30:31], 0, v[24:25]
	v_lshl_add_u64 v[34:35], s[0:1], 0, v[24:25]
	s_nop 1
	v_mov_b32_e32 v28, v200
	v_mov_b32_e32 v29, v201
	v_mov_b32_e32 v30, v202
	v_mov_b32_e32 v31, v203
	v_mul_f32_e32 v22, 0xbfb8aa3b, v22
	s_nop 1
	v_mov_b32_e32 v24, v204
	v_mov_b32_e32 v25, v205
	v_mov_b32_e32 v26, v206
	v_mov_b32_e32 v27, v207
	v_mul_f32_e32 v23, 0xbfb8aa3b, v23
	v_pk_mul_f32 v[20:21], v[20:21], v[32:33] op_sel_hi:[1,0]
	v_pk_mul_f32 v[18:19], v[18:19], v[32:33] op_sel_hi:[1,0]
	v_exp_f32_e32 v22, v22
	v_exp_f32_e32 v23, v23
	v_mul_f32_e32 v16, 0xbfb8aa3b, v16
	v_mul_f32_e32 v17, 0xbfb8aa3b, v17
	v_mul_f32_e32 v20, 0xbfb8aa3b, v20
	v_mul_f32_e32 v21, 0xbfb8aa3b, v21
	v_exp_f32_e32 v16, v16
	v_exp_f32_e32 v17, v17
	v_mul_f32_e32 v18, 0xbfb8aa3b, v18
	v_mul_f32_e32 v19, 0xbfb8aa3b, v19
	v_exp_f32_e32 v20, v20
	v_exp_f32_e32 v21, v21
	v_exp_f32_e32 v18, v18
	v_exp_f32_e32 v19, v19
	v_add_f32_e32 v22, 1.0, v22
	v_add_f32_e32 v23, 1.0, v23
	v_rcp_f32_e32 v22, v22
	v_rcp_f32_e32 v23, v23
	v_add_f32_e32 v16, 1.0, v16
	v_add_f32_e32 v17, 1.0, v17
	v_add_f32_e32 v20, 1.0, v20
	v_add_f32_e32 v21, 1.0, v21
	v_rcp_f32_e32 v16, v16
	v_rcp_f32_e32 v17, v17
	v_add_f32_e32 v18, 1.0, v18
	v_add_f32_e32 v19, 1.0, v19
	v_rcp_f32_e32 v20, v20
	v_rcp_f32_e32 v21, v21
	v_rcp_f32_e32 v18, v18
	v_rcp_f32_e32 v19, v19
	s_mov_b64 s[2:3], 0x58000
	v_lshlrev_b32_e32 v32, 16, v28
	v_and_b32_e32 v33, 0xffff0000, v28
	v_lshlrev_b32_e32 v36, 16, v24
	v_and_b32_e32 v37, 0xffff0000, v24
	v_lshlrev_b32_e32 v28, 16, v29
	v_and_b32_e32 v29, 0xffff0000, v29
	v_lshlrev_b32_e32 v24, 16, v25
	v_and_b32_e32 v25, 0xffff0000, v25
	v_pk_fma_f32 v[22:23], v[22:23], v[28:29], v[24:25]
	v_lshlrev_b32_e32 v24, 16, v30
	v_and_b32_e32 v25, 0xffff0000, v30
	v_lshlrev_b32_e32 v28, 16, v26
	v_and_b32_e32 v29, 0xffff0000, v26
	v_pk_fma_f32 v[24:25], v[16:17], v[24:25], v[28:29]
	v_lshlrev_b32_e32 v16, 16, v31
	v_and_b32_e32 v17, 0xffff0000, v31
	v_lshlrev_b32_e32 v26, 16, v27
	v_and_b32_e32 v27, 0xffff0000, v27
	v_pk_fma_f32 v[20:21], v[20:21], v[32:33], v[36:37]
	v_pk_fma_f32 v[26:27], v[18:19], v[16:17], v[26:27]
	v_cvt_pk_bf16_f32 v16, v20, v21
	v_cvt_pk_bf16_f32 v17, v22, v23
	v_cvt_pk_bf16_f32 v18, v24, v25
	v_cvt_pk_bf16_f32 v19, v26, v27
	global_store_dwordx4 v[34:35], v[16:19], off
	s_nop 1
	v_mov_b32_e32 v16, v248
	v_lshl_add_u64 v[22:23], v[158:159], 0, s[2:3]
	v_lshl_add_u64 v[18:19], s[30:31], 0, v[22:23]
	v_lshl_add_u64 v[26:27], s[0:1], 0, v[22:23]
	s_waitcnt vmcnt(5)
; __device__ __forceinline__ unsigned cvt_pk_bf16(float lo, float hi) { const f32x2_cv v = {lo, hi}; const bf16x2_cv b = __builtin_convertvector(v, bf16x2_cv); return __builtin_bit_cast(unsigned, b); }
; __device__ __forceinline__ float sigm(float x) { return __builtin_amdgcn_rcpf(1.0f + __expf(-x)); }
; __device__ __forceinline__ float lo16(unsigned w) { return __uint_as_float(w << 16); }
; template <class Epi, class Sched, bool STAMP = false>
; __device__ __forceinline__ void gemm_phase(PG8_LAS unsigned char* lds, const Gemm g, const Sched& S, const Epi& E, unsigned long long* stamps) {
;     ...
;         if constexpr (!Epi::AFTER_DRAIN) { E(acc, cur, wr, wc, fr, fq); S.done(cur); }
;         if (!has_next) break;
;     __device__ __forceinline__ void operator()(const f32x4 (&acc)[2][2][4][2], const pg8::Unit& u, int wr, int wc, int fr, int fq) const {
;         const int row0 = u.pm * 256 + wr * 64 + fr, col0 = u.pn * 256 + wc * 32 + 8 * fq;
; #pragma unroll
;         for (int ai = 0; ai < 2; ++ai)
; #pragma unroll
;             for (int m = 0; m < 4; ++m) {
;                 const int row = row0 + ai * 128 + m * 16;
;                 const float s = rstd_of(rowss, row);
; #pragma unroll
;                 for (int bj = 0; bj < 2; ++bj) {
;                     const size_t off = (size_t)row * 1024 + col0 + bj * 128;
;                     const u32x4 tv = *(const u32x4*)(Tm + off);
;                     u32x4 pv = (u32x4){0u, 0u, 0u, 0u};
;                     if (ACC) pv = *(const u32x4*)(M + off);
;                     const f32x4 a0 = acc[ai][bj][m][0] * s, a1 = acc[ai][bj][m][1] * s;
;                     float o[8];
;                     o[0] = sigm(a0[0]) * lo16(tv.x); o[1] = sigm(a0[1]) * hi16(tv.x); o[2] = sigm(a0[2]) * lo16(tv.y); o[3] = sigm(a0[3]) * hi16(tv.y);
;                     o[4] = sigm(a1[0]) * lo16(tv.z); o[5] = sigm(a1[1]) * hi16(tv.z); o[6] = sigm(a1[2]) * lo16(tv.w); o[7] = sigm(a1[3]) * hi16(tv.w);
;                     if (ACC) { o[0] += lo16(pv.x); o[1] += hi16(pv.x); o[2] += lo16(pv.y); o[3] += hi16(pv.y); o[4] += lo16(pv.z); o[5] += hi16(pv.z); o[6] += lo16(pv.w); o[7] += hi16(pv.w); }
;                     u32x4 w; w.x = cvt_pk_bf16(o[0], o[1]); w.y = cvt_pk_bf16(o[2], o[3]); w.z = cvt_pk_bf16(o[4], o[5]); w.w = cvt_pk_bf16(o[6], o[7]);
;                     *(u32x4*)(M + off) = w; } }
	s_nop 1
	v_mov_b32_e32 v18, v208
	v_mov_b32_e32 v19, v209
	v_mov_b32_e32 v20, v210
	v_mov_b32_e32 v21, v211
	s_mov_b64 s[2:3], 0x58100
	s_nop 1
	v_mov_b32_e32 v22, v212
	v_mov_b32_e32 v23, v213
	v_mov_b32_e32 v24, v214
	v_mov_b32_e32 v25, v215
	v_fmamk_f32 v16, v16, 0x3a800000, v187
	v_cmp_gt_f32_e32 vcc, s67, v16
	v_mul_f32_e32 v17, 0x4b800000, v16
	v_lshlrev_b32_e32 v28, 16, v18
	v_cndmask_b32_e32 v16, v16, v17, vcc
	v_rsq_f32_e32 v16, v16
	v_and_b32_e32 v29, 0xffff0000, v18
	v_lshlrev_b32_e32 v30, 16, v22
	v_and_b32_e32 v31, 0xffff0000, v22
	v_mul_f32_e32 v17, 0x45800000, v16
	v_cndmask_b32_e32 v16, v16, v17, vcc
	v_pk_mul_f32 v[14:15], v[14:15], v[16:17] op_sel_hi:[1,0]
	v_pk_mul_f32 v[8:9], v[8:9], v[16:17] op_sel_hi:[1,0]
	v_mul_f32_e32 v14, 0xbfb8aa3b, v14
	v_mul_f32_e32 v15, 0xbfb8aa3b, v15
	v_pk_mul_f32 v[12:13], v[12:13], v[16:17] op_sel_hi:[1,0]
	v_pk_mul_f32 v[10:11], v[10:11], v[16:17] op_sel_hi:[1,0]
	v_exp_f32_e32 v14, v14
	v_exp_f32_e32 v15, v15
	v_mul_f32_e32 v8, 0xbfb8aa3b, v8
	v_mul_f32_e32 v9, 0xbfb8aa3b, v9
	v_mul_f32_e32 v12, 0xbfb8aa3b, v12
	v_mul_f32_e32 v13, 0xbfb8aa3b, v13
	v_exp_f32_e32 v8, v8
	v_exp_f32_e32 v9, v9
	v_mul_f32_e32 v10, 0xbfb8aa3b, v10
	v_mul_f32_e32 v11, 0xbfb8aa3b, v11
	v_exp_f32_e32 v12, v12
	v_exp_f32_e32 v13, v13
	v_exp_f32_e32 v10, v10
	v_exp_f32_e32 v11, v11
	v_add_f32_e32 v14, 1.0, v14
	v_add_f32_e32 v15, 1.0, v15
	v_rcp_f32_e32 v14, v14
	v_rcp_f32_e32 v15, v15
	v_add_f32_e32 v8, 1.0, v8
	v_add_f32_e32 v9, 1.0, v9
	v_add_f32_e32 v12, 1.0, v12
	v_add_f32_e32 v13, 1.0, v13
	v_rcp_f32_e32 v8, v8
	v_rcp_f32_e32 v9, v9
	v_add_f32_e32 v10, 1.0, v10
	v_add_f32_e32 v11, 1.0, v11
	v_rcp_f32_e32 v12, v12
	v_rcp_f32_e32 v13, v13
	v_rcp_f32_e32 v10, v10
	v_rcp_f32_e32 v11, v11
	v_lshlrev_b32_e32 v18, 16, v19
	v_and_b32_e32 v19, 0xffff0000, v19
	v_lshlrev_b32_e32 v22, 16, v23
	v_and_b32_e32 v23, 0xffff0000, v23
	v_pk_fma_f32 v[14:15], v[14:15], v[18:19], v[22:23]
	v_lshlrev_b32_e32 v18, 16, v20
	v_and_b32_e32 v19, 0xffff0000, v20
	v_lshlrev_b32_e32 v22, 16, v24
	v_and_b32_e32 v23, 0xffff0000, v24
	v_pk_fma_f32 v[18:19], v[8:9], v[18:19], v[22:23]
	v_lshlrev_b32_e32 v8, 16, v21
	v_and_b32_e32 v9, 0xffff0000, v21
	v_lshlrev_b32_e32 v20, 16, v25
	v_and_b32_e32 v21, 0xffff0000, v25
	v_pk_fma_f32 v[12:13], v[12:13], v[28:29], v[30:31]
	v_pk_fma_f32 v[20:21], v[10:11], v[8:9], v[20:21]
	v_cvt_pk_bf16_f32 v8, v12, v13
	v_cvt_pk_bf16_f32 v9, v14, v15
	v_cvt_pk_bf16_f32 v10, v18, v19
	v_cvt_pk_bf16_f32 v11, v20, v21
	global_store_dwordx4 v[26:27], v[8:11], off
	v_pk_mul_f32 v[6:7], v[6:7], v[16:17] op_sel_hi:[1,0]
	v_pk_mul_f32 v[0:1], v[0:1], v[16:17] op_sel_hi:[1,0]
	v_lshl_add_u64 v[8:9], v[158:159], 0, s[2:3]
	v_lshl_add_u64 v[10:11], s[30:31], 0, v[8:9]
	v_lshl_add_u64 v[18:19], s[0:1], 0, v[8:9]
	s_nop 1
	v_mov_b32_e32 v12, v216
	v_mov_b32_e32 v13, v217
	v_mov_b32_e32 v14, v218
	v_mov_b32_e32 v15, v219
	v_mul_f32_e32 v6, 0xbfb8aa3b, v6
	s_nop 1
	v_mov_b32_e32 v8, v220
	v_mov_b32_e32 v9, v221
	v_mov_b32_e32 v10, v222
	v_mov_b32_e32 v11, v223
	v_mul_f32_e32 v7, 0xbfb8aa3b, v7
	v_pk_mul_f32 v[4:5], v[4:5], v[16:17] op_sel_hi:[1,0]
	v_pk_mul_f32 v[2:3], v[2:3], v[16:17] op_sel_hi:[1,0]
	v_exp_f32_e32 v6, v6
	v_exp_f32_e32 v7, v7
	v_mul_f32_e32 v0, 0xbfb8aa3b, v0
	v_mul_f32_e32 v1, 0xbfb8aa3b, v1
	v_mul_f32_e32 v4, 0xbfb8aa3b, v4
	v_mul_f32_e32 v5, 0xbfb8aa3b, v5
	v_exp_f32_e32 v0, v0
	v_exp_f32_e32 v1, v1
	v_mul_f32_e32 v2, 0xbfb8aa3b, v2
	v_mul_f32_e32 v3, 0xbfb8aa3b, v3
	v_exp_f32_e32 v4, v4
	v_exp_f32_e32 v5, v5
	v_exp_f32_e32 v2, v2
	v_exp_f32_e32 v3, v3
	v_add_f32_e32 v6, 1.0, v6
	v_add_f32_e32 v7, 1.0, v7
	v_rcp_f32_e32 v6, v6
	v_rcp_f32_e32 v7, v7
	v_add_f32_e32 v0, 1.0, v0
	v_add_f32_e32 v1, 1.0, v1
	v_add_f32_e32 v4, 1.0, v4
	v_add_f32_e32 v5, 1.0, v5
	v_rcp_f32_e32 v0, v0
	v_rcp_f32_e32 v1, v1
	v_add_f32_e32 v2, 1.0, v2
	v_add_f32_e32 v3, 1.0, v3
	v_rcp_f32_e32 v4, v4
	v_rcp_f32_e32 v5, v5
	v_rcp_f32_e32 v2, v2
	v_rcp_f32_e32 v3, v3
	s_and_b64 vcc, exec, s[38:39]
	s_mov_b32 s3, s26
	s_mov_b32 s2, s12
	v_lshlrev_b32_e32 v16, 16, v12
	v_and_b32_e32 v17, 0xffff0000, v12
	v_lshlrev_b32_e32 v20, 16, v8
	v_and_b32_e32 v21, 0xffff0000, v8
	v_lshlrev_b32_e32 v12, 16, v13
	v_and_b32_e32 v13, 0xffff0000, v13
	v_lshlrev_b32_e32 v8, 16, v9
	v_and_b32_e32 v9, 0xffff0000, v9
	v_pk_fma_f32 v[6:7], v[6:7], v[12:13], v[8:9]
	v_lshlrev_b32_e32 v8, 16, v14
	v_and_b32_e32 v9, 0xffff0000, v14
	v_lshlrev_b32_e32 v12, 16, v10
	v_and_b32_e32 v13, 0xffff0000, v10
	v_pk_fma_f32 v[8:9], v[0:1], v[8:9], v[12:13]
	v_lshlrev_b32_e32 v0, 16, v15
	v_and_b32_e32 v1, 0xffff0000, v15
	v_lshlrev_b32_e32 v10, 16, v11
	v_and_b32_e32 v11, 0xffff0000, v11
	v_pk_fma_f32 v[4:5], v[4:5], v[16:17], v[20:21]
	v_pk_fma_f32 v[10:11], v[2:3], v[0:1], v[10:11]
	v_cvt_pk_bf16_f32 v0, v4, v5
	v_cvt_pk_bf16_f32 v1, v6, v7
	v_cvt_pk_bf16_f32 v2, v8, v9
	v_cvt_pk_bf16_f32 v3, v10, v11
	global_store_dwordx4 v[18:19], v[0:3], off
	s_cbranch_vccz .LBB0_346
	s_cmpk_gt_u32 s70, 0xff
	s_cbranch_scc1 .LBB0_357
	s_barrier
